# GEMM K-loop stage DMAs rebalanced 4/4/4/4 per phase (was 2/6/2/6) in all four GEMM loops: SA(1,0) moved to ph1, SA(0,0) to ph3, vmcnt(6) in ph2/ph4
# speedup vs baseline: 1.0087x; 1.0087x over previous
; #define PG8_STAGE(bufoff, gbase, voff) do { _Pragma("unroll") for (int _i = 0; _i < 2; ++_i) \
;         __builtin_amdgcn_global_load_lds((const unsigned*)((const char*)(gbase) + (voff)[_i]), (LAS unsigned*)(lds + (bufoff) + ldsw + _i * 8192), 16, 0, 0); } while (0)
; #define PG8_LDA(dst, b, h) do { _Pragma("unroll") for (int m = 0; m < 4; ++m) _Pragma("unroll") for (int k = 0; k < 2; ++k) dst[m][k] = *(const LAS bf16x8*)(lds + PG8_SA(b, h) + aoff + m * 2048 + k * 1024); } while (0)
; #define PG8_LDB(dst, b, h) do { _Pragma("unroll") for (int n = 0; n < 2; ++n) _Pragma("unroll") for (int k = 0; k < 2; ++k) dst[n][k] = *(const LAS bf16x8*)(lds + PG8_SB(b, h) + boff + n * 2048 + k * 1024); } while (0)
; #define PG8_MMA(ai, bj, At, Bt) do { __builtin_amdgcn_s_setprio(3); _Pragma("unroll") for (int m = 0; m < 4; ++m) _Pragma("unroll") for (int n = 0; n < 2; ++n) _Pragma("unroll") for (int k = 0; k < 2; ++k) \
;         acc[ai][bj][m][n] = __builtin_amdgcn_mfma_f32_16x16x32_bf16(Bt[n][k], At[m][k], acc[ai][bj][m][n], 0, 0, 0); __builtin_amdgcn_s_setprio(0); } while (0)
; #define PG8_WAIT_V(n) asm volatile("s_waitcnt vmcnt(" #n ")" ::: "memory")
; #define PG8_WAIT_L(n) asm volatile("s_waitcnt lgkmcnt(" #n ")" ::: "memory")
; #define PG8_BAR __builtin_amdgcn_s_barrier()
; #define PG8_SCHED __builtin_amdgcn_sched_barrier(0)
; template <class Epi, class Sched, bool ALIGN_EPI = false, bool SP2 = false>
; __device__ __forceinline__ void gemm_phase(LAS unsigned char* lds, const Gemm g, const Sched& S, const Epi& E) {
;     ...
;             PG8_LDB(B0, 0, 0); PG8_LDB(B1, 0, 1); PG8_SCHED; PG8_LDA(At, 0, 0); PG8_STAGE(PG8_SA(1, 1), a1 + hsA, voffA);
;             PG8_WAIT_V(8); PG8_WAIT_L(0); PG8_BAR; PG8_MMA(0, 0, At, B0); PG8_MMA(0, 1, At, B1); PG8_BAR; PG8_SCHED;
;             PG8_LDA(At, 0, 1); PG8_STAGE(PG8_SB(0, 0), b2, voffB); PG8_STAGE(PG8_SB(0, 1), b2 + hsB, voffB); PG8_STAGE(PG8_SA(0, 0), a2, voffA);
;             PG8_WAIT_V(8); PG8_WAIT_L(0); PG8_BAR; PG8_MMA(1, 0, At, B0); PG8_MMA(1, 1, At, B1); PG8_BAR; PG8_SCHED;
.LBB0_64:
	ds_read_b128 v[128:131], v158
	ds_read_b128 v[150:153], v158 offset:1024
	ds_read_b128 v[166:169], v158 offset:2048
	ds_read_b128 v[170:173], v158 offset:3072
	ds_read_b128 v[174:177], v159
	ds_read_b128 v[178:181], v159 offset:1024
	ds_read_b128 v[182:185], v159 offset:2048
	ds_read_b128 v[186:189], v159 offset:3072
	s_add_u32 s6, s4, 0xffefc080
	s_addc_u32 s7, s5, -1
	s_cmp_eq_u32 s91, 60
	s_cselect_b32 s63, s59, s7
	s_cselect_b32 s62, s58, s6
	s_cselect_b32 s7, s61, s90
	s_cselect_b32 s6, s60, s89
	s_sub_u32 s100, s4, 0x104000
	s_subb_u32 s101, s5, 0
	v_lshl_add_u64 v[242:243], s[100:101], 0, v[132:133]
	s_mov_b32 m0, s76
	v_lshl_add_u64 v[244:245], s[100:101], 0, v[136:137]
	global_load_lds_dwordx4 v[242:243], off
	s_mov_b32 m0, s77
	s_nop 0
	global_load_lds_dwordx4 v[244:245], off
	v_lshl_add_u64 v[226:227], s[4:5], 0, v[142:143]
	s_add_i32 m0, s68, 0xc000
	ds_read_b128 v[190:193], v160
	ds_read_b128 v[194:197], v160 offset:1024
	ds_read_b128 v[198:201], v160 offset:2048
	ds_read_b128 v[206:209], v160 offset:3072
	ds_read_b128 v[210:213], v160 offset:4096
	ds_read_b128 v[214:217], v160 offset:5120
	ds_read_b128 v[218:221], v160 offset:6144
	ds_read_b128 v[222:225], v160 offset:7168
	global_load_lds_dwordx4 v[226:227], off
	v_lshl_add_u64 v[226:227], s[4:5], 0, v[144:145]
	s_add_i32 m0, s68, 0xe000
	s_nop 0
	global_load_lds_dwordx4 v[226:227], off
	s_waitcnt vmcnt(8)
	s_waitcnt lgkmcnt(0)
	s_barrier
	s_setprio 3
	s_waitcnt lgkmcnt(0)
	v_mfma_f32_16x16x32_bf16 v[124:127], v[128:131], v[190:193], v[124:127]
	v_mfma_f32_16x16x32_bf16 v[120:123], v[166:169], v[190:193], v[120:123]
	v_mfma_f32_16x16x32_bf16 v[108:111], v[128:131], v[198:201], v[108:111]
	v_mfma_f32_16x16x32_bf16 v[104:107], v[166:169], v[198:201], v[104:107]
	v_mfma_f32_16x16x32_bf16 v[92:95], v[128:131], v[210:213], v[92:95]
	v_mfma_f32_16x16x32_bf16 v[88:91], v[166:169], v[210:213], v[88:91]
	v_mfma_f32_16x16x32_bf16 v[76:79], v[128:131], v[218:221], v[76:79]
	v_mfma_f32_16x16x32_bf16 v[72:75], v[166:169], v[218:221], v[72:75]
	v_mfma_f32_16x16x32_bf16 v[124:127], v[150:153], v[194:197], v[124:127]
	v_mfma_f32_16x16x32_bf16 v[120:123], v[170:173], v[194:197], v[120:123]
	v_mfma_f32_16x16x32_bf16 v[108:111], v[150:153], v[206:209], v[108:111]
	v_mfma_f32_16x16x32_bf16 v[104:107], v[170:173], v[206:209], v[104:107]
	v_mfma_f32_16x16x32_bf16 v[92:95], v[150:153], v[214:217], v[92:95]
	v_mfma_f32_16x16x32_bf16 v[88:91], v[170:173], v[214:217], v[88:91]
	v_mfma_f32_16x16x32_bf16 v[76:79], v[150:153], v[222:225], v[76:79]
	v_mfma_f32_16x16x32_bf16 v[72:75], v[170:173], v[222:225], v[72:75]
	s_setprio 0
	s_setprio 3
	v_mfma_f32_16x16x32_bf16 v[116:119], v[174:177], v[190:193], v[116:119]
	v_mfma_f32_16x16x32_bf16 v[112:115], v[182:185], v[190:193], v[112:115]
	v_mfma_f32_16x16x32_bf16 v[100:103], v[174:177], v[198:201], v[100:103]
	v_mfma_f32_16x16x32_bf16 v[96:99], v[182:185], v[198:201], v[96:99]
	v_mfma_f32_16x16x32_bf16 v[84:87], v[174:177], v[210:213], v[84:87]
	v_mfma_f32_16x16x32_bf16 v[80:83], v[182:185], v[210:213], v[80:83]
	v_mfma_f32_16x16x32_bf16 v[68:71], v[174:177], v[218:221], v[68:71]
	v_mfma_f32_16x16x32_bf16 v[64:67], v[182:185], v[218:221], v[64:67]
	v_mfma_f32_16x16x32_bf16 v[116:119], v[178:181], v[194:197], v[116:119]
	v_mfma_f32_16x16x32_bf16 v[112:115], v[186:189], v[194:197], v[112:115]
	v_mfma_f32_16x16x32_bf16 v[100:103], v[178:181], v[206:209], v[100:103]
	v_mfma_f32_16x16x32_bf16 v[96:99], v[186:189], v[206:209], v[96:99]
	v_mfma_f32_16x16x32_bf16 v[84:87], v[178:181], v[214:217], v[84:87]
	v_mfma_f32_16x16x32_bf16 v[80:83], v[186:189], v[214:217], v[80:83]
	v_mfma_f32_16x16x32_bf16 v[68:71], v[178:181], v[222:225], v[68:71]
	v_mfma_f32_16x16x32_bf16 v[64:67], v[186:189], v[222:225], v[64:67]
	s_setprio 0
	s_barrier
	s_add_i32 s92, s82, s67
	v_lshl_add_u64 v[226:227], s[6:7], 0, v[134:135]
	s_mov_b32 m0, s92
	ds_read_b128 v[190:193], v160 offset:16384
	ds_read_b128 v[194:197], v160 offset:17408
	ds_read_b128 v[198:201], v160 offset:18432
	ds_read_b128 v[206:209], v160 offset:19456
	ds_read_b128 v[210:213], v160 offset:20480
	ds_read_b128 v[214:217], v160 offset:21504
	ds_read_b128 v[218:221], v160 offset:22528
	ds_read_b128 v[222:225], v160 offset:23552
	global_load_lds_dwordx4 v[226:227], off
	s_add_i32 m0, s92, 0x2000
	s_add_u32 s92, s6, 0x41000
	v_lshl_add_u64 v[228:229], s[6:7], 0, v[138:139]
	s_addc_u32 s93, s7, 0
	s_add_i32 s94, s83, s67
	global_load_lds_dwordx4 v[228:229], off
	v_lshl_add_u64 v[230:231], s[92:93], 0, v[134:135]
	s_mov_b32 m0, s94
	s_nop 0
	global_load_lds_dwordx4 v[230:231], off
	v_lshl_add_u64 v[230:231], s[92:93], 0, v[138:139]
	s_add_i32 m0, s94, 0x2000
	s_nop 0
	global_load_lds_dwordx4 v[230:231], off
	s_waitcnt vmcnt(6)
	s_waitcnt lgkmcnt(0)
	s_barrier
; #define PG8_STAGE(bufoff, gbase, voff) do { _Pragma("unroll") for (int _i = 0; _i < 2; ++_i) \
;         __builtin_amdgcn_global_load_lds((const unsigned*)((const char*)(gbase) + (voff)[_i]), (LAS unsigned*)(lds + (bufoff) + ldsw + _i * 8192), 16, 0, 0); } while (0)
; #define PG8_LDA(dst, b, h) do { _Pragma("unroll") for (int m = 0; m < 4; ++m) _Pragma("unroll") for (int k = 0; k < 2; ++k) dst[m][k] = *(const LAS bf16x8*)(lds + PG8_SA(b, h) + aoff + m * 2048 + k * 1024); } while (0)
; #define PG8_LDB(dst, b, h) do { _Pragma("unroll") for (int n = 0; n < 2; ++n) _Pragma("unroll") for (int k = 0; k < 2; ++k) dst[n][k] = *(const LAS bf16x8*)(lds + PG8_SB(b, h) + boff + n * 2048 + k * 1024); } while (0)
; #define PG8_MMA(ai, bj, At, Bt) do { __builtin_amdgcn_s_setprio(3); _Pragma("unroll") for (int m = 0; m < 4; ++m) _Pragma("unroll") for (int n = 0; n < 2; ++n) _Pragma("unroll") for (int k = 0; k < 2; ++k) \
;         acc[ai][bj][m][n] = __builtin_amdgcn_mfma_f32_16x16x32_bf16(Bt[n][k], At[m][k], acc[ai][bj][m][n], 0, 0, 0); __builtin_amdgcn_s_setprio(0); } while (0)
; #define PG8_WAIT_V(n) asm volatile("s_waitcnt vmcnt(" #n ")" ::: "memory")
; #define PG8_WAIT_L(n) asm volatile("s_waitcnt lgkmcnt(" #n ")" ::: "memory")
; #define PG8_BAR __builtin_amdgcn_s_barrier()
; #define PG8_SCHED __builtin_amdgcn_sched_barrier(0)
; template <class Epi, class Sched, bool ALIGN_EPI = false, bool SP2 = false>
; __device__ __forceinline__ void gemm_phase(LAS unsigned char* lds, const Gemm g, const Sched& S, const Epi& E) {
;     ...
;             PG8_WAIT_V(8); PG8_WAIT_L(0); PG8_BAR; PG8_MMA(1, 0, At, B0); PG8_MMA(1, 1, At, B1); PG8_BAR; PG8_SCHED;
;             PG8_LDB(B0, 1, 0); PG8_LDB(B1, 1, 1); PG8_SCHED; PG8_LDA(At, 1, 0); PG8_STAGE(PG8_SA(0, 1), a2 + hsA, voffA);
;             PG8_WAIT_V(8); PG8_WAIT_L(0); PG8_BAR; PG8_MMA(0, 0, At, B0); PG8_MMA(0, 1, At, B1); PG8_BAR; PG8_SCHED;
	s_setprio 3
	s_waitcnt lgkmcnt(0)
	v_mfma_f32_16x16x32_bf16 v[60:63], v[128:131], v[190:193], v[60:63]
	v_mfma_f32_16x16x32_bf16 v[56:59], v[166:169], v[190:193], v[56:59]
	v_mfma_f32_16x16x32_bf16 v[44:47], v[128:131], v[198:201], v[44:47]
	v_mfma_f32_16x16x32_bf16 v[40:43], v[166:169], v[198:201], v[40:43]
	v_mfma_f32_16x16x32_bf16 v[28:31], v[128:131], v[210:213], v[28:31]
	v_mfma_f32_16x16x32_bf16 v[24:27], v[166:169], v[210:213], v[24:27]
	v_mfma_f32_16x16x32_bf16 v[12:15], v[128:131], v[218:221], v[12:15]
	v_mfma_f32_16x16x32_bf16 v[8:11], v[166:169], v[218:221], v[8:11]
	v_mfma_f32_16x16x32_bf16 v[60:63], v[150:153], v[194:197], v[60:63]
	v_mfma_f32_16x16x32_bf16 v[56:59], v[170:173], v[194:197], v[56:59]
	v_mfma_f32_16x16x32_bf16 v[44:47], v[150:153], v[206:209], v[44:47]
	v_mfma_f32_16x16x32_bf16 v[40:43], v[170:173], v[206:209], v[40:43]
	v_mfma_f32_16x16x32_bf16 v[28:31], v[150:153], v[214:217], v[28:31]
	v_mfma_f32_16x16x32_bf16 v[24:27], v[170:173], v[214:217], v[24:27]
	v_mfma_f32_16x16x32_bf16 v[12:15], v[150:153], v[222:225], v[12:15]
	v_mfma_f32_16x16x32_bf16 v[8:11], v[170:173], v[222:225], v[8:11]
	s_setprio 0
	s_setprio 3
	v_mfma_f32_16x16x32_bf16 v[52:55], v[174:177], v[190:193], v[52:55]
	v_mfma_f32_16x16x32_bf16 v[48:51], v[182:185], v[190:193], v[48:51]
	v_mfma_f32_16x16x32_bf16 v[36:39], v[174:177], v[198:201], v[36:39]
	v_mfma_f32_16x16x32_bf16 v[32:35], v[182:185], v[198:201], v[32:35]
	v_mfma_f32_16x16x32_bf16 v[20:23], v[174:177], v[210:213], v[20:23]
	v_mfma_f32_16x16x32_bf16 v[16:19], v[182:185], v[210:213], v[16:19]
	v_mfma_f32_16x16x32_bf16 v[4:7], v[174:177], v[218:221], v[4:7]
	v_mfma_f32_16x16x32_bf16 v[0:3], v[182:185], v[218:221], v[0:3]
	v_mfma_f32_16x16x32_bf16 v[52:55], v[178:181], v[194:197], v[52:55]
	v_mfma_f32_16x16x32_bf16 v[48:51], v[186:189], v[194:197], v[48:51]
	v_mfma_f32_16x16x32_bf16 v[36:39], v[178:181], v[206:209], v[36:39]
	v_mfma_f32_16x16x32_bf16 v[32:35], v[186:189], v[206:209], v[32:35]
	v_mfma_f32_16x16x32_bf16 v[20:23], v[178:181], v[214:217], v[20:23]
	v_mfma_f32_16x16x32_bf16 v[16:19], v[186:189], v[214:217], v[16:19]
	v_mfma_f32_16x16x32_bf16 v[4:7], v[178:181], v[222:225], v[4:7]
	v_mfma_f32_16x16x32_bf16 v[0:3], v[186:189], v[222:225], v[0:3]
	s_setprio 0
	s_barrier
	s_add_i32 s92, 0, 0x18000
	v_add_u32_e32 v165, s92, v156
	s_add_i32 s93, 0, 0x1c000
	ds_read_b128 v[128:131], v165
	ds_read_b128 v[150:153], v165 offset:1024
	ds_read_b128 v[166:169], v165 offset:2048
	ds_read_b128 v[170:173], v165 offset:3072
	v_add_u32_e32 v165, s93, v156
	ds_read_b128 v[174:177], v165
	ds_read_b128 v[178:181], v165 offset:1024
	ds_read_b128 v[182:185], v165 offset:2048
	ds_read_b128 v[186:189], v165 offset:3072
	v_lshl_add_u64 v[242:243], s[62:63], 0, v[132:133]
	s_mov_b32 m0, s68
	v_lshl_add_u64 v[244:245], s[62:63], 0, v[136:137]
	global_load_lds_dwordx4 v[242:243], off
	s_mov_b32 m0, s69
	s_nop 0
	global_load_lds_dwordx4 v[244:245], off
	s_add_u32 s62, s62, 0x104000
	s_addc_u32 s63, s63, 0
	s_mov_b32 m0, s70
	v_lshl_add_u64 v[234:235], s[62:63], 0, v[132:133]
	ds_read_b128 v[190:193], v160 offset:32768
	ds_read_b128 v[194:197], v160 offset:33792
	ds_read_b128 v[198:201], v160 offset:34816
	ds_read_b128 v[206:209], v160 offset:35840
	ds_read_b128 v[210:213], v160 offset:36864
	ds_read_b128 v[214:217], v160 offset:37888
	ds_read_b128 v[218:221], v160 offset:38912
	ds_read_b128 v[222:225], v160 offset:39936
	global_load_lds_dwordx4 v[234:235], off
	v_lshl_add_u64 v[234:235], s[62:63], 0, v[136:137]
	s_mov_b32 m0, s71
	s_nop 0
	global_load_lds_dwordx4 v[234:235], off
	s_waitcnt vmcnt(8)
	s_waitcnt lgkmcnt(0)
	s_barrier
; #define PG8_STAGE(bufoff, gbase, voff) do { _Pragma("unroll") for (int _i = 0; _i < 2; ++_i) \
;         __builtin_amdgcn_global_load_lds((const unsigned*)((const char*)(gbase) + (voff)[_i]), (LAS unsigned*)(lds + (bufoff) + ldsw + _i * 8192), 16, 0, 0); } while (0)
; #define PG8_LDA(dst, b, h) do { _Pragma("unroll") for (int m = 0; m < 4; ++m) _Pragma("unroll") for (int k = 0; k < 2; ++k) dst[m][k] = *(const LAS bf16x8*)(lds + PG8_SA(b, h) + aoff + m * 2048 + k * 1024); } while (0)
; #define PG8_MMA(ai, bj, At, Bt) do { __builtin_amdgcn_s_setprio(3); _Pragma("unroll") for (int m = 0; m < 4; ++m) _Pragma("unroll") for (int n = 0; n < 2; ++n) _Pragma("unroll") for (int k = 0; k < 2; ++k) \
;         acc[ai][bj][m][n] = __builtin_amdgcn_mfma_f32_16x16x32_bf16(Bt[n][k], At[m][k], acc[ai][bj][m][n], 0, 0, 0); __builtin_amdgcn_s_setprio(0); } while (0)
; #define PG8_WAIT_V(n) asm volatile("s_waitcnt vmcnt(" #n ")" ::: "memory")
; #define PG8_WAIT_L(n) asm volatile("s_waitcnt lgkmcnt(" #n ")" ::: "memory")
; #define PG8_BAR __builtin_amdgcn_s_barrier()
; #define PG8_SCHED __builtin_amdgcn_sched_barrier(0)
; template <class Epi, class Sched, bool ALIGN_EPI = false, bool SP2 = false>
; __device__ __forceinline__ void gemm_phase(LAS unsigned char* lds, const Gemm g, const Sched& S, const Epi& E) {
;     ...
;         for (int t = 0; t < nt; t += 2) {
;     ...
;             PG8_WAIT_V(8); PG8_WAIT_L(0); PG8_BAR; PG8_MMA(0, 0, At, B0); PG8_MMA(0, 1, At, B1); PG8_BAR; PG8_SCHED;
;             PG8_LDA(At, 1, 1); PG8_STAGE(PG8_SB(1, 0), b3, voffB); PG8_STAGE(PG8_SB(1, 1), b3 + hsB, voffB); PG8_STAGE(PG8_SA(1, 0), a3, voffA);
;             PG8_WAIT_V(8); PG8_WAIT_L(0); PG8_BAR; PG8_MMA(1, 0, At, B0); PG8_MMA(1, 1, At, B1); PG8_BAR; PG8_SCHED;
	s_setprio 3
	s_waitcnt lgkmcnt(0)
	v_mfma_f32_16x16x32_bf16 v[124:127], v[128:131], v[190:193], v[124:127]
	v_mfma_f32_16x16x32_bf16 v[120:123], v[166:169], v[190:193], v[120:123]
	v_mfma_f32_16x16x32_bf16 v[108:111], v[128:131], v[198:201], v[108:111]
	v_mfma_f32_16x16x32_bf16 v[104:107], v[166:169], v[198:201], v[104:107]
	v_mfma_f32_16x16x32_bf16 v[92:95], v[128:131], v[210:213], v[92:95]
	v_mfma_f32_16x16x32_bf16 v[88:91], v[166:169], v[210:213], v[88:91]
	v_mfma_f32_16x16x32_bf16 v[76:79], v[128:131], v[218:221], v[76:79]
	v_mfma_f32_16x16x32_bf16 v[72:75], v[166:169], v[218:221], v[72:75]
	v_mfma_f32_16x16x32_bf16 v[124:127], v[150:153], v[194:197], v[124:127]
	v_mfma_f32_16x16x32_bf16 v[120:123], v[170:173], v[194:197], v[120:123]
	v_mfma_f32_16x16x32_bf16 v[108:111], v[150:153], v[206:209], v[108:111]
	v_mfma_f32_16x16x32_bf16 v[104:107], v[170:173], v[206:209], v[104:107]
	v_mfma_f32_16x16x32_bf16 v[92:95], v[150:153], v[214:217], v[92:95]
	v_mfma_f32_16x16x32_bf16 v[88:91], v[170:173], v[214:217], v[88:91]
	v_mfma_f32_16x16x32_bf16 v[76:79], v[150:153], v[222:225], v[76:79]
	v_mfma_f32_16x16x32_bf16 v[72:75], v[170:173], v[222:225], v[72:75]
	s_setprio 0
	s_setprio 3
	v_mfma_f32_16x16x32_bf16 v[116:119], v[174:177], v[190:193], v[116:119]
	v_mfma_f32_16x16x32_bf16 v[112:115], v[182:185], v[190:193], v[112:115]
	v_mfma_f32_16x16x32_bf16 v[100:103], v[174:177], v[198:201], v[100:103]
	v_mfma_f32_16x16x32_bf16 v[96:99], v[182:185], v[198:201], v[96:99]
	v_mfma_f32_16x16x32_bf16 v[84:87], v[174:177], v[210:213], v[84:87]
	v_mfma_f32_16x16x32_bf16 v[80:83], v[182:185], v[210:213], v[80:83]
	v_mfma_f32_16x16x32_bf16 v[68:71], v[174:177], v[218:221], v[68:71]
	v_mfma_f32_16x16x32_bf16 v[64:67], v[182:185], v[218:221], v[64:67]
	v_mfma_f32_16x16x32_bf16 v[116:119], v[178:181], v[194:197], v[116:119]
	v_mfma_f32_16x16x32_bf16 v[112:115], v[186:189], v[194:197], v[112:115]
	v_mfma_f32_16x16x32_bf16 v[100:103], v[178:181], v[206:209], v[100:103]
	v_mfma_f32_16x16x32_bf16 v[96:99], v[186:189], v[206:209], v[96:99]
	v_mfma_f32_16x16x32_bf16 v[84:87], v[178:181], v[214:217], v[84:87]
	v_mfma_f32_16x16x32_bf16 v[80:83], v[186:189], v[214:217], v[80:83]
	v_mfma_f32_16x16x32_bf16 v[68:71], v[178:181], v[222:225], v[68:71]
	v_mfma_f32_16x16x32_bf16 v[64:67], v[186:189], v[222:225], v[64:67]
	s_setprio 0
	s_barrier
	s_add_i32 s62, s92, s67
	v_lshl_add_u64 v[226:227], v[226:227], 0, s[46:47]
	s_mov_b32 m0, s62
	ds_read_b128 v[190:193], v160 offset:49152
	ds_read_b128 v[194:197], v160 offset:50176
	ds_read_b128 v[198:201], v160 offset:51200
	ds_read_b128 v[206:209], v160 offset:52224
	ds_read_b128 v[210:213], v160 offset:53248
	ds_read_b128 v[214:217], v160 offset:54272
	ds_read_b128 v[218:221], v160 offset:55296
	ds_read_b128 v[222:225], v160 offset:56320
	global_load_lds_dwordx4 v[226:227], off
	s_add_i32 m0, s62, 0x2000
	s_add_u32 s6, s6, 0x41080
	v_lshl_add_u64 v[226:227], v[228:229], 0, s[46:47]
	s_addc_u32 s7, s7, 0
	s_add_i32 s62, s93, s67
	global_load_lds_dwordx4 v[226:227], off
	v_lshl_add_u64 v[226:227], s[6:7], 0, v[134:135]
	s_mov_b32 m0, s62
	s_nop 0
	global_load_lds_dwordx4 v[226:227], off
	v_lshl_add_u64 v[226:227], s[6:7], 0, v[138:139]
	s_add_i32 m0, s62, 0x2000
	s_nop 0
	global_load_lds_dwordx4 v[226:227], off
	s_waitcnt vmcnt(6)
	s_waitcnt lgkmcnt(0)
	s_barrier
	s_setprio 3
	s_waitcnt lgkmcnt(0)
	v_mfma_f32_16x16x32_bf16 v[60:63], v[128:131], v[190:193], v[60:63]
	v_mfma_f32_16x16x32_bf16 v[56:59], v[166:169], v[190:193], v[56:59]
	v_mfma_f32_16x16x32_bf16 v[44:47], v[128:131], v[198:201], v[44:47]
	v_mfma_f32_16x16x32_bf16 v[40:43], v[166:169], v[198:201], v[40:43]
	v_mfma_f32_16x16x32_bf16 v[28:31], v[128:131], v[210:213], v[28:31]
	v_mfma_f32_16x16x32_bf16 v[24:27], v[166:169], v[210:213], v[24:27]
	v_mfma_f32_16x16x32_bf16 v[12:15], v[128:131], v[218:221], v[12:15]
	v_mfma_f32_16x16x32_bf16 v[8:11], v[166:169], v[218:221], v[8:11]
	v_mfma_f32_16x16x32_bf16 v[60:63], v[150:153], v[194:197], v[60:63]
	v_mfma_f32_16x16x32_bf16 v[56:59], v[170:173], v[194:197], v[56:59]
	v_mfma_f32_16x16x32_bf16 v[44:47], v[150:153], v[206:209], v[44:47]
	v_mfma_f32_16x16x32_bf16 v[40:43], v[170:173], v[206:209], v[40:43]
	v_mfma_f32_16x16x32_bf16 v[28:31], v[150:153], v[214:217], v[28:31]
	v_mfma_f32_16x16x32_bf16 v[24:27], v[170:173], v[214:217], v[24:27]
	v_mfma_f32_16x16x32_bf16 v[12:15], v[150:153], v[222:225], v[12:15]
	v_mfma_f32_16x16x32_bf16 v[8:11], v[170:173], v[222:225], v[8:11]
	s_setprio 0
	s_setprio 3
	v_mfma_f32_16x16x32_bf16 v[52:55], v[174:177], v[190:193], v[52:55]
	v_mfma_f32_16x16x32_bf16 v[48:51], v[182:185], v[190:193], v[48:51]
	v_mfma_f32_16x16x32_bf16 v[36:39], v[174:177], v[198:201], v[36:39]
	v_mfma_f32_16x16x32_bf16 v[32:35], v[182:185], v[198:201], v[32:35]
	v_mfma_f32_16x16x32_bf16 v[20:23], v[174:177], v[210:213], v[20:23]
	v_mfma_f32_16x16x32_bf16 v[16:19], v[182:185], v[210:213], v[16:19]
	v_mfma_f32_16x16x32_bf16 v[4:7], v[174:177], v[218:221], v[4:7]
	v_mfma_f32_16x16x32_bf16 v[0:3], v[182:185], v[218:221], v[0:3]
	v_mfma_f32_16x16x32_bf16 v[52:55], v[178:181], v[194:197], v[52:55]
	v_mfma_f32_16x16x32_bf16 v[48:51], v[186:189], v[194:197], v[48:51]
	v_mfma_f32_16x16x32_bf16 v[36:39], v[178:181], v[206:209], v[36:39]
	v_mfma_f32_16x16x32_bf16 v[32:35], v[186:189], v[206:209], v[32:35]
	v_mfma_f32_16x16x32_bf16 v[20:23], v[178:181], v[214:217], v[20:23]
	v_mfma_f32_16x16x32_bf16 v[16:19], v[186:189], v[214:217], v[16:19]
	v_mfma_f32_16x16x32_bf16 v[4:7], v[178:181], v[222:225], v[4:7]
	v_mfma_f32_16x16x32_bf16 v[0:3], v[186:189], v[222:225], v[0:3]
	s_setprio 0
	s_barrier
	s_add_i32 s91, s91, 2
	s_add_u32 s4, s4, 0x100
	s_addc_u32 s5, s5, 0
	s_add_u32 s89, s89, 0x100
	s_addc_u32 s90, s90, 0
	s_cmp_gt_u32 s91, 61
	s_cbranch_scc0 .LBB0_64
	s_and_b64 vcc, exec, s[50:51]
	s_cbranch_vccz .LBB0_67
	s_barrier

; #define PG8_STAGE(bufoff, gbase, voff) do { _Pragma("unroll") for (int _i = 0; _i < 2; ++_i) \
;         __builtin_amdgcn_global_load_lds((const unsigned*)((const char*)(gbase) + (voff)[_i]), (LAS unsigned*)(lds + (bufoff) + ldsw + _i * 8192), 16, 0, 0); } while (0)
; #define PG8_LDA(dst, b, h) do { _Pragma("unroll") for (int m = 0; m < 4; ++m) _Pragma("unroll") for (int k = 0; k < 2; ++k) dst[m][k] = *(const LAS bf16x8*)(lds + PG8_SA(b, h) + aoff + m * 2048 + k * 1024); } while (0)
; #define PG8_LDB(dst, b, h) do { _Pragma("unroll") for (int n = 0; n < 2; ++n) _Pragma("unroll") for (int k = 0; k < 2; ++k) dst[n][k] = *(const LAS bf16x8*)(lds + PG8_SB(b, h) + boff + n * 2048 + k * 1024); } while (0)
; #define PG8_MMA(ai, bj, At, Bt) do { __builtin_amdgcn_s_setprio(3); _Pragma("unroll") for (int m = 0; m < 4; ++m) _Pragma("unroll") for (int n = 0; n < 2; ++n) _Pragma("unroll") for (int k = 0; k < 2; ++k) \
;         acc[ai][bj][m][n] = __builtin_amdgcn_mfma_f32_16x16x32_bf16(Bt[n][k], At[m][k], acc[ai][bj][m][n], 0, 0, 0); __builtin_amdgcn_s_setprio(0); } while (0)
; #define PG8_WAIT_V(n) asm volatile("s_waitcnt vmcnt(" #n ")" ::: "memory")
; #define PG8_WAIT_L(n) asm volatile("s_waitcnt lgkmcnt(" #n ")" ::: "memory")
; #define PG8_BAR __builtin_amdgcn_s_barrier()
; #define PG8_SCHED __builtin_amdgcn_sched_barrier(0)
; template <class Epi, class Sched, bool ALIGN_EPI = false, bool SP2 = false>
; __device__ __forceinline__ void gemm_phase(LAS unsigned char* lds, const Gemm g, const Sched& S, const Epi& E) {
;     ...
;             PG8_LDB(B0, 0, 0); PG8_LDB(B1, 0, 1); PG8_SCHED; PG8_LDA(At, 0, 0); PG8_STAGE(PG8_SA(1, 1), a1 + hsA, voffA);
;             PG8_WAIT_V(8); PG8_WAIT_L(0); PG8_BAR; PG8_MMA(0, 0, At, B0); PG8_MMA(0, 1, At, B1); PG8_BAR; PG8_SCHED;
;             PG8_LDA(At, 0, 1); PG8_STAGE(PG8_SB(0, 0), b2, voffB); PG8_STAGE(PG8_SB(0, 1), b2 + hsB, voffB); PG8_STAGE(PG8_SA(0, 0), a2, voffA);
;             PG8_WAIT_V(8); PG8_WAIT_L(0); PG8_BAR; PG8_MMA(1, 0, At, B0); PG8_MMA(1, 1, At, B1); PG8_BAR; PG8_SCHED;
.LBB0_234:
	v_add_u32_e32 v1, s88, v194
	ds_read_b128 v[84:87], v1
	ds_read_b128 v[96:99], v1 offset:1024
	ds_read_b128 v[140:143], v1 offset:2048
	ds_read_b128 v[144:147], v1 offset:3072
	v_add_u32_e32 v1, s89, v194
	s_add_u32 s4, s64, s66
	ds_read_b128 v[152:155], v1
	ds_read_b128 v[156:159], v1 offset:1024
	ds_read_b128 v[160:163], v1 offset:2048
	ds_read_b128 v[182:185], v1 offset:3072
	s_addc_u32 s5, s65, s67
	s_add_u32 s4, s4, 0x100
	s_addc_u32 s5, s5, 0
	s_add_u32 s96, s93, s66
	s_addc_u32 s97, s94, s67
	s_cmpk_eq_i32 s66, 0x1f00
	s_cselect_b32 s9, s59, s5
	s_cselect_b32 s8, s91, s4
	s_cselect_b32 s5, s61, s97
	s_cselect_b32 s4, s60, s96
	s_sub_u32 s100, s66, 0x100000
	s_subb_u32 s101, s67, 0
	v_lshl_add_u64 v[242:243], v[148:149], 0, s[100:101]
	s_mov_b32 m0, s81
	v_lshl_add_u64 v[244:245], v[150:151], 0, s[100:101]
	global_load_lds_dwordx4 v[242:243], off
	s_mov_b32 m0, s82
	s_nop 0
	global_load_lds_dwordx4 v[244:245], off
	v_lshl_add_u64 v[2:3], v[148:149], 0, s[66:67]
	s_add_i32 m0, s41, 0xc000
	ds_read_b128 v[186:189], v198
	ds_read_b128 v[208:211], v198 offset:1024
	ds_read_b128 v[212:215], v198 offset:2048
	ds_read_b128 v[216:219], v198 offset:3072
	ds_read_b128 v[220:223], v198 offset:4096
	ds_read_b128 v[224:227], v198 offset:5120
	ds_read_b128 v[228:231], v198 offset:6144
	ds_read_b128 v[232:235], v198 offset:7168
	global_load_lds_dwordx4 v[2:3], off
	v_lshl_add_u64 v[2:3], v[150:151], 0, s[66:67]
	s_add_i32 m0, s41, 0xe000
	s_nop 0
	global_load_lds_dwordx4 v[2:3], off
	s_waitcnt vmcnt(8)
	s_waitcnt lgkmcnt(0)
	s_barrier
	s_setprio 3
	s_waitcnt lgkmcnt(0)
	v_mfma_f32_16x16x32_bf16 v[136:139], v[84:87], v[186:189], v[136:139]
	v_mfma_f32_16x16x32_bf16 v[132:135], v[140:143], v[186:189], v[132:135]
	v_mfma_f32_16x16x32_bf16 v[120:123], v[84:87], v[212:215], v[120:123]
	v_mfma_f32_16x16x32_bf16 v[116:119], v[140:143], v[212:215], v[116:119]
	v_mfma_f32_16x16x32_bf16 v[104:107], v[84:87], v[220:223], v[104:107]
	v_mfma_f32_16x16x32_bf16 v[100:103], v[140:143], v[220:223], v[100:103]
	v_mfma_f32_16x16x32_bf16 v[80:83], v[84:87], v[228:231], v[80:83]
	v_mfma_f32_16x16x32_bf16 v[76:79], v[140:143], v[228:231], v[76:79]
	v_mfma_f32_16x16x32_bf16 v[136:139], v[96:99], v[208:211], v[136:139]
	v_mfma_f32_16x16x32_bf16 v[132:135], v[144:147], v[208:211], v[132:135]
	v_mfma_f32_16x16x32_bf16 v[120:123], v[96:99], v[216:219], v[120:123]
	v_mfma_f32_16x16x32_bf16 v[116:119], v[144:147], v[216:219], v[116:119]
	v_mfma_f32_16x16x32_bf16 v[104:107], v[96:99], v[224:227], v[104:107]
	v_mfma_f32_16x16x32_bf16 v[100:103], v[144:147], v[224:227], v[100:103]
	v_mfma_f32_16x16x32_bf16 v[80:83], v[96:99], v[232:235], v[80:83]
	v_mfma_f32_16x16x32_bf16 v[76:79], v[144:147], v[232:235], v[76:79]
	s_setprio 0
	s_setprio 3
	v_mfma_f32_16x16x32_bf16 v[128:131], v[152:155], v[186:189], v[128:131]
	v_mfma_f32_16x16x32_bf16 v[124:127], v[160:163], v[186:189], v[124:127]
	v_mfma_f32_16x16x32_bf16 v[112:115], v[152:155], v[212:215], v[112:115]
	v_mfma_f32_16x16x32_bf16 v[108:111], v[160:163], v[212:215], v[108:111]
	v_mfma_f32_16x16x32_bf16 v[92:95], v[152:155], v[220:223], v[92:95]
	v_mfma_f32_16x16x32_bf16 v[88:91], v[160:163], v[220:223], v[88:91]
	v_mfma_f32_16x16x32_bf16 v[72:75], v[152:155], v[228:231], v[72:75]
	v_mfma_f32_16x16x32_bf16 v[68:71], v[160:163], v[228:231], v[68:71]
	v_mfma_f32_16x16x32_bf16 v[128:131], v[156:159], v[208:211], v[128:131]
	v_mfma_f32_16x16x32_bf16 v[124:127], v[182:185], v[208:211], v[124:127]
	v_mfma_f32_16x16x32_bf16 v[112:115], v[156:159], v[216:219], v[112:115]
	v_mfma_f32_16x16x32_bf16 v[108:111], v[182:185], v[216:219], v[108:111]
	v_mfma_f32_16x16x32_bf16 v[92:95], v[156:159], v[224:227], v[92:95]
	v_mfma_f32_16x16x32_bf16 v[88:91], v[182:185], v[224:227], v[88:91]
	v_mfma_f32_16x16x32_bf16 v[72:75], v[156:159], v[232:235], v[72:75]
	v_mfma_f32_16x16x32_bf16 v[68:71], v[182:185], v[232:235], v[68:71]
	s_setprio 0
	s_barrier
	s_add_i32 s96, s88, s31
	v_lshl_add_u64 v[190:191], s[4:5], 0, v[166:167]
	s_mov_b32 m0, s96
	ds_read_b128 v[186:189], v198 offset:16384
	ds_read_b128 v[208:211], v198 offset:17408
	ds_read_b128 v[212:215], v198 offset:18432
	ds_read_b128 v[216:219], v198 offset:19456
	ds_read_b128 v[220:223], v198 offset:20480
	ds_read_b128 v[224:227], v198 offset:21504
	ds_read_b128 v[228:231], v198 offset:22528
	ds_read_b128 v[232:235], v198 offset:23552
	global_load_lds_dwordx4 v[190:191], off
	s_add_i32 m0, s96, 0x2000
	s_add_u32 s96, s4, 0x104000
	v_lshl_add_u64 v[236:237], s[4:5], 0, v[170:171]
	s_addc_u32 s97, s5, 0
	s_add_i32 s98, s89, s31
	global_load_lds_dwordx4 v[236:237], off
	v_lshl_add_u64 v[2:3], s[96:97], 0, v[166:167]
	s_mov_b32 m0, s98
	s_nop 0
	global_load_lds_dwordx4 v[2:3], off
	v_lshl_add_u64 v[2:3], s[96:97], 0, v[170:171]
	s_add_i32 m0, s98, 0x2000
	s_nop 0
	global_load_lds_dwordx4 v[2:3], off
	s_waitcnt vmcnt(6)
	s_waitcnt lgkmcnt(0)
	s_barrier
; #define PG8_STAGE(bufoff, gbase, voff) do { _Pragma("unroll") for (int _i = 0; _i < 2; ++_i) \
;         __builtin_amdgcn_global_load_lds((const unsigned*)((const char*)(gbase) + (voff)[_i]), (LAS unsigned*)(lds + (bufoff) + ldsw + _i * 8192), 16, 0, 0); } while (0)
; #define PG8_LDA(dst, b, h) do { _Pragma("unroll") for (int m = 0; m < 4; ++m) _Pragma("unroll") for (int k = 0; k < 2; ++k) dst[m][k] = *(const LAS bf16x8*)(lds + PG8_SA(b, h) + aoff + m * 2048 + k * 1024); } while (0)
; #define PG8_LDB(dst, b, h) do { _Pragma("unroll") for (int n = 0; n < 2; ++n) _Pragma("unroll") for (int k = 0; k < 2; ++k) dst[n][k] = *(const LAS bf16x8*)(lds + PG8_SB(b, h) + boff + n * 2048 + k * 1024); } while (0)
; #define PG8_MMA(ai, bj, At, Bt) do { __builtin_amdgcn_s_setprio(3); _Pragma("unroll") for (int m = 0; m < 4; ++m) _Pragma("unroll") for (int n = 0; n < 2; ++n) _Pragma("unroll") for (int k = 0; k < 2; ++k) \
;         acc[ai][bj][m][n] = __builtin_amdgcn_mfma_f32_16x16x32_bf16(Bt[n][k], At[m][k], acc[ai][bj][m][n], 0, 0, 0); __builtin_amdgcn_s_setprio(0); } while (0)
; #define PG8_WAIT_V(n) asm volatile("s_waitcnt vmcnt(" #n ")" ::: "memory")
; #define PG8_WAIT_L(n) asm volatile("s_waitcnt lgkmcnt(" #n ")" ::: "memory")
; #define PG8_BAR __builtin_amdgcn_s_barrier()
; #define PG8_SCHED __builtin_amdgcn_sched_barrier(0)
; template <class Epi, class Sched, bool ALIGN_EPI = false, bool SP2 = false>
; __device__ __forceinline__ void gemm_phase(LAS unsigned char* lds, const Gemm g, const Sched& S, const Epi& E) {
;     ...
;             PG8_WAIT_V(8); PG8_WAIT_L(0); PG8_BAR; PG8_MMA(1, 0, At, B0); PG8_MMA(1, 1, At, B1); PG8_BAR; PG8_SCHED;
;             PG8_LDB(B0, 1, 0); PG8_LDB(B1, 1, 1); PG8_SCHED; PG8_LDA(At, 1, 0); PG8_STAGE(PG8_SA(0, 1), a2 + hsA, voffA);
;             PG8_WAIT_V(8); PG8_WAIT_L(0); PG8_BAR; PG8_MMA(0, 0, At, B0); PG8_MMA(0, 1, At, B1); PG8_BAR; PG8_SCHED;
	s_setprio 3
	s_waitcnt lgkmcnt(0)
	v_mfma_f32_16x16x32_bf16 v[64:67], v[84:87], v[186:189], v[64:67]
	v_mfma_f32_16x16x32_bf16 v[60:63], v[140:143], v[186:189], v[60:63]
	v_mfma_f32_16x16x32_bf16 v[48:51], v[84:87], v[212:215], v[48:51]
	v_mfma_f32_16x16x32_bf16 v[44:47], v[140:143], v[212:215], v[44:47]
	v_mfma_f32_16x16x32_bf16 v[32:35], v[84:87], v[220:223], v[32:35]
	v_mfma_f32_16x16x32_bf16 v[28:31], v[140:143], v[220:223], v[28:31]
	v_mfma_f32_16x16x32_bf16 v[16:19], v[84:87], v[228:231], v[16:19]
	v_mfma_f32_16x16x32_bf16 v[12:15], v[140:143], v[228:231], v[12:15]
	v_mfma_f32_16x16x32_bf16 v[64:67], v[96:99], v[208:211], v[64:67]
	v_mfma_f32_16x16x32_bf16 v[60:63], v[144:147], v[208:211], v[60:63]
	v_mfma_f32_16x16x32_bf16 v[48:51], v[96:99], v[216:219], v[48:51]
	v_mfma_f32_16x16x32_bf16 v[44:47], v[144:147], v[216:219], v[44:47]
	v_mfma_f32_16x16x32_bf16 v[32:35], v[96:99], v[224:227], v[32:35]
	v_mfma_f32_16x16x32_bf16 v[28:31], v[144:147], v[224:227], v[28:31]
	v_mfma_f32_16x16x32_bf16 v[16:19], v[96:99], v[232:235], v[16:19]
	v_mfma_f32_16x16x32_bf16 v[12:15], v[144:147], v[232:235], v[12:15]
	s_setprio 0
	s_setprio 3
	v_mfma_f32_16x16x32_bf16 v[56:59], v[152:155], v[186:189], v[56:59]
	v_mfma_f32_16x16x32_bf16 v[52:55], v[160:163], v[186:189], v[52:55]
	v_mfma_f32_16x16x32_bf16 v[40:43], v[152:155], v[212:215], v[40:43]
	v_mfma_f32_16x16x32_bf16 v[36:39], v[160:163], v[212:215], v[36:39]
	v_mfma_f32_16x16x32_bf16 v[24:27], v[152:155], v[220:223], v[24:27]
	v_mfma_f32_16x16x32_bf16 v[20:23], v[160:163], v[220:223], v[20:23]
	v_mfma_f32_16x16x32_bf16 v[8:11], v[152:155], v[228:231], v[8:11]
	v_mfma_f32_16x16x32_bf16 v[2:5], v[160:163], v[228:231], v[4:7]
	v_mfma_f32_16x16x32_bf16 v[56:59], v[156:159], v[208:211], v[56:59]
	v_mfma_f32_16x16x32_bf16 v[52:55], v[182:185], v[208:211], v[52:55]
	v_mfma_f32_16x16x32_bf16 v[40:43], v[156:159], v[216:219], v[40:43]
	v_mfma_f32_16x16x32_bf16 v[36:39], v[182:185], v[216:219], v[36:39]
	v_mfma_f32_16x16x32_bf16 v[24:27], v[156:159], v[224:227], v[24:27]
	v_mfma_f32_16x16x32_bf16 v[20:23], v[182:185], v[224:227], v[20:23]
	v_mfma_f32_16x16x32_bf16 v[8:11], v[156:159], v[232:235], v[8:11]
	v_mfma_f32_16x16x32_bf16 v[2:5], v[182:185], v[232:235], v[2:5]
	s_setprio 0
	s_barrier
	s_add_i32 s96, 0, 0x18000
	v_add_u32_e32 v1, s96, v194
	s_add_i32 s97, 0, 0x1c000
	ds_read_b128 v[84:87], v1
	ds_read_b128 v[96:99], v1 offset:1024
	ds_read_b128 v[140:143], v1 offset:2048
	ds_read_b128 v[144:147], v1 offset:3072
	v_add_u32_e32 v1, s97, v194
	ds_read_b128 v[152:155], v1
	ds_read_b128 v[156:159], v1 offset:1024
	ds_read_b128 v[160:163], v1 offset:2048
	ds_read_b128 v[182:185], v1 offset:3072
	v_lshl_add_u64 v[242:243], s[8:9], 0, v[164:165]
	s_mov_b32 m0, s41
	v_lshl_add_u64 v[244:245], s[8:9], 0, v[168:169]
	global_load_lds_dwordx4 v[242:243], off
	s_mov_b32 m0, s68
	s_nop 0
	global_load_lds_dwordx4 v[244:245], off
	s_add_u32 s8, s8, 0x100000
	s_addc_u32 s9, s9, 0
	s_mov_b32 m0, s69
	v_lshl_add_u64 v[6:7], s[8:9], 0, v[164:165]
	ds_read_b128 v[186:189], v198 offset:32768
	ds_read_b128 v[208:211], v198 offset:33792
	ds_read_b128 v[212:215], v198 offset:34816
	ds_read_b128 v[216:219], v198 offset:35840
	ds_read_b128 v[220:223], v198 offset:36864
	ds_read_b128 v[224:227], v198 offset:37888
	ds_read_b128 v[228:231], v198 offset:38912
	ds_read_b128 v[232:235], v198 offset:39936
	global_load_lds_dwordx4 v[6:7], off
	v_lshl_add_u64 v[6:7], s[8:9], 0, v[168:169]
	s_mov_b32 m0, s70
	s_nop 0
	global_load_lds_dwordx4 v[6:7], off
	s_waitcnt vmcnt(8)
	s_waitcnt lgkmcnt(0)
	s_barrier
; #define PG8_STAGE(bufoff, gbase, voff) do { _Pragma("unroll") for (int _i = 0; _i < 2; ++_i) \
;         __builtin_amdgcn_global_load_lds((const unsigned*)((const char*)(gbase) + (voff)[_i]), (LAS unsigned*)(lds + (bufoff) + ldsw + _i * 8192), 16, 0, 0); } while (0)
; #define PG8_LDA(dst, b, h) do { _Pragma("unroll") for (int m = 0; m < 4; ++m) _Pragma("unroll") for (int k = 0; k < 2; ++k) dst[m][k] = *(const LAS bf16x8*)(lds + PG8_SA(b, h) + aoff + m * 2048 + k * 1024); } while (0)
; #define PG8_MMA(ai, bj, At, Bt) do { __builtin_amdgcn_s_setprio(3); _Pragma("unroll") for (int m = 0; m < 4; ++m) _Pragma("unroll") for (int n = 0; n < 2; ++n) _Pragma("unroll") for (int k = 0; k < 2; ++k) \
;         acc[ai][bj][m][n] = __builtin_amdgcn_mfma_f32_16x16x32_bf16(Bt[n][k], At[m][k], acc[ai][bj][m][n], 0, 0, 0); __builtin_amdgcn_s_setprio(0); } while (0)
; #define PG8_WAIT_V(n) asm volatile("s_waitcnt vmcnt(" #n ")" ::: "memory")
; #define PG8_WAIT_L(n) asm volatile("s_waitcnt lgkmcnt(" #n ")" ::: "memory")
; #define PG8_BAR __builtin_amdgcn_s_barrier()
; #define PG8_SCHED __builtin_amdgcn_sched_barrier(0)
; template <class Epi, class Sched, bool ALIGN_EPI = false, bool SP2 = false>
; __device__ __forceinline__ void gemm_phase(LAS unsigned char* lds, const Gemm g, const Sched& S, const Epi& E) {
;     ...
;         for (int t = 0; t < nt; t += 2) {
;     ...
;             PG8_WAIT_V(8); PG8_WAIT_L(0); PG8_BAR; PG8_MMA(0, 0, At, B0); PG8_MMA(0, 1, At, B1); PG8_BAR; PG8_SCHED;
;             PG8_LDA(At, 1, 1); PG8_STAGE(PG8_SB(1, 0), b3, voffB); PG8_STAGE(PG8_SB(1, 1), b3 + hsB, voffB); PG8_STAGE(PG8_SA(1, 0), a3, voffA);
;             PG8_WAIT_V(8); PG8_WAIT_L(0); PG8_BAR; PG8_MMA(1, 0, At, B0); PG8_MMA(1, 1, At, B1); PG8_BAR; PG8_SCHED;
	s_setprio 3
	s_waitcnt lgkmcnt(0)
	v_mfma_f32_16x16x32_bf16 v[136:139], v[84:87], v[186:189], v[136:139]
	v_mfma_f32_16x16x32_bf16 v[132:135], v[140:143], v[186:189], v[132:135]
	v_mfma_f32_16x16x32_bf16 v[120:123], v[84:87], v[212:215], v[120:123]
	v_mfma_f32_16x16x32_bf16 v[116:119], v[140:143], v[212:215], v[116:119]
	v_mfma_f32_16x16x32_bf16 v[104:107], v[84:87], v[220:223], v[104:107]
	v_mfma_f32_16x16x32_bf16 v[100:103], v[140:143], v[220:223], v[100:103]
	v_mfma_f32_16x16x32_bf16 v[80:83], v[84:87], v[228:231], v[80:83]
	v_mfma_f32_16x16x32_bf16 v[76:79], v[140:143], v[228:231], v[76:79]
	v_mfma_f32_16x16x32_bf16 v[136:139], v[96:99], v[208:211], v[136:139]
	v_mfma_f32_16x16x32_bf16 v[132:135], v[144:147], v[208:211], v[132:135]
	v_mfma_f32_16x16x32_bf16 v[120:123], v[96:99], v[216:219], v[120:123]
	v_mfma_f32_16x16x32_bf16 v[116:119], v[144:147], v[216:219], v[116:119]
	v_mfma_f32_16x16x32_bf16 v[104:107], v[96:99], v[224:227], v[104:107]
	v_mfma_f32_16x16x32_bf16 v[100:103], v[144:147], v[224:227], v[100:103]
	v_mfma_f32_16x16x32_bf16 v[80:83], v[96:99], v[232:235], v[80:83]
	v_mfma_f32_16x16x32_bf16 v[76:79], v[144:147], v[232:235], v[76:79]
	s_setprio 0
	s_setprio 3
	v_mfma_f32_16x16x32_bf16 v[128:131], v[152:155], v[186:189], v[128:131]
	v_mfma_f32_16x16x32_bf16 v[124:127], v[160:163], v[186:189], v[124:127]
	v_mfma_f32_16x16x32_bf16 v[112:115], v[152:155], v[212:215], v[112:115]
	v_mfma_f32_16x16x32_bf16 v[108:111], v[160:163], v[212:215], v[108:111]
	v_mfma_f32_16x16x32_bf16 v[92:95], v[152:155], v[220:223], v[92:95]
	v_mfma_f32_16x16x32_bf16 v[88:91], v[160:163], v[220:223], v[88:91]
	v_mfma_f32_16x16x32_bf16 v[72:75], v[152:155], v[228:231], v[72:75]
	v_mfma_f32_16x16x32_bf16 v[68:71], v[160:163], v[228:231], v[68:71]
	v_mfma_f32_16x16x32_bf16 v[128:131], v[156:159], v[208:211], v[128:131]
	v_mfma_f32_16x16x32_bf16 v[124:127], v[182:185], v[208:211], v[124:127]
	v_mfma_f32_16x16x32_bf16 v[112:115], v[156:159], v[216:219], v[112:115]
	v_mfma_f32_16x16x32_bf16 v[108:111], v[182:185], v[216:219], v[108:111]
	v_mfma_f32_16x16x32_bf16 v[92:95], v[156:159], v[224:227], v[92:95]
	v_mfma_f32_16x16x32_bf16 v[88:91], v[182:185], v[224:227], v[88:91]
	v_mfma_f32_16x16x32_bf16 v[72:75], v[156:159], v[232:235], v[72:75]
	v_mfma_f32_16x16x32_bf16 v[68:71], v[182:185], v[232:235], v[68:71]
	s_setprio 0
	s_barrier
	s_add_i32 s8, s96, s31
	v_lshl_add_u64 v[6:7], v[190:191], 0, s[24:25]
	s_mov_b32 m0, s8
	ds_read_b128 v[186:189], v198 offset:49152
	ds_read_b128 v[208:211], v198 offset:50176
	ds_read_b128 v[212:215], v198 offset:51200
	ds_read_b128 v[216:219], v198 offset:52224
	ds_read_b128 v[220:223], v198 offset:53248
	ds_read_b128 v[224:227], v198 offset:54272
	ds_read_b128 v[228:231], v198 offset:55296
	ds_read_b128 v[232:235], v198 offset:56320
	global_load_lds_dwordx4 v[6:7], off
	s_add_i32 m0, s8, 0x2000
	s_add_u32 s4, s4, 0x104080
	v_lshl_add_u64 v[6:7], v[236:237], 0, s[24:25]
	s_addc_u32 s5, s5, 0
	s_add_i32 s8, s97, s31
	global_load_lds_dwordx4 v[6:7], off
	v_lshl_add_u64 v[6:7], s[4:5], 0, v[166:167]
	s_mov_b32 m0, s8
	s_nop 0
	global_load_lds_dwordx4 v[6:7], off
	v_lshl_add_u64 v[6:7], s[4:5], 0, v[170:171]
	s_add_i32 m0, s8, 0x2000
	s_nop 0
	global_load_lds_dwordx4 v[6:7], off
	s_waitcnt vmcnt(6)
	s_waitcnt lgkmcnt(0)
	s_barrier
	s_setprio 3
	s_waitcnt lgkmcnt(0)
	v_mfma_f32_16x16x32_bf16 v[64:67], v[84:87], v[186:189], v[64:67]
	v_mfma_f32_16x16x32_bf16 v[60:63], v[140:143], v[186:189], v[60:63]
	v_mfma_f32_16x16x32_bf16 v[48:51], v[84:87], v[212:215], v[48:51]
	v_mfma_f32_16x16x32_bf16 v[44:47], v[140:143], v[212:215], v[44:47]
	v_mfma_f32_16x16x32_bf16 v[32:35], v[84:87], v[220:223], v[32:35]
	v_mfma_f32_16x16x32_bf16 v[28:31], v[140:143], v[220:223], v[28:31]
	v_mfma_f32_16x16x32_bf16 v[16:19], v[84:87], v[228:231], v[16:19]
	v_mfma_f32_16x16x32_bf16 v[12:15], v[140:143], v[228:231], v[12:15]
	v_mfma_f32_16x16x32_bf16 v[64:67], v[96:99], v[208:211], v[64:67]
	v_mfma_f32_16x16x32_bf16 v[60:63], v[144:147], v[208:211], v[60:63]
	v_mfma_f32_16x16x32_bf16 v[48:51], v[96:99], v[216:219], v[48:51]
	v_mfma_f32_16x16x32_bf16 v[44:47], v[144:147], v[216:219], v[44:47]
	v_mfma_f32_16x16x32_bf16 v[32:35], v[96:99], v[224:227], v[32:35]
	v_mfma_f32_16x16x32_bf16 v[28:31], v[144:147], v[224:227], v[28:31]
	v_mfma_f32_16x16x32_bf16 v[16:19], v[96:99], v[232:235], v[16:19]
	v_mfma_f32_16x16x32_bf16 v[12:15], v[144:147], v[232:235], v[12:15]
	s_setprio 0
	s_setprio 3
	v_mfma_f32_16x16x32_bf16 v[56:59], v[152:155], v[186:189], v[56:59]
	v_mfma_f32_16x16x32_bf16 v[52:55], v[160:163], v[186:189], v[52:55]
	v_mfma_f32_16x16x32_bf16 v[40:43], v[152:155], v[212:215], v[40:43]
	v_mfma_f32_16x16x32_bf16 v[36:39], v[160:163], v[212:215], v[36:39]
	v_mfma_f32_16x16x32_bf16 v[24:27], v[152:155], v[220:223], v[24:27]
	v_mfma_f32_16x16x32_bf16 v[20:23], v[160:163], v[220:223], v[20:23]
	v_mfma_f32_16x16x32_bf16 v[6:9], v[152:155], v[228:231], v[8:11]
	v_mfma_f32_16x16x32_bf16 v[2:5], v[160:163], v[228:231], v[2:5]
	v_mfma_f32_16x16x32_bf16 v[56:59], v[156:159], v[208:211], v[56:59]
	v_mfma_f32_16x16x32_bf16 v[52:55], v[182:185], v[208:211], v[52:55]
	v_mfma_f32_16x16x32_bf16 v[40:43], v[156:159], v[216:219], v[40:43]
	v_mfma_f32_16x16x32_bf16 v[36:39], v[182:185], v[216:219], v[36:39]
	v_mfma_f32_16x16x32_bf16 v[24:27], v[156:159], v[224:227], v[24:27]
	v_mfma_f32_16x16x32_bf16 v[20:23], v[182:185], v[224:227], v[20:23]
	v_mfma_f32_16x16x32_bf16 v[8:11], v[156:159], v[232:235], v[6:9]
	v_mfma_f32_16x16x32_bf16 v[4:7], v[182:185], v[232:235], v[2:5]
	s_setprio 0
	s_barrier
	s_add_i32 s95, s95, 2
	s_add_u32 s66, s66, 0x100
	s_addc_u32 s67, s67, 0
	s_cmp_gt_u32 s95, 61
	s_cbranch_scc1 .LBB0_237

; #define PG8_STAGE(bufoff, gbase, voff) do { _Pragma("unroll") for (int _i = 0; _i < 2; ++_i) \
;         __builtin_amdgcn_global_load_lds((const unsigned*)((const char*)(gbase) + (voff)[_i]), (LAS unsigned*)(lds + (bufoff) + ldsw + _i * 8192), 16, 0, 0); } while (0)
; #define PG8_LDA(dst, b, h) do { _Pragma("unroll") for (int m = 0; m < 4; ++m) _Pragma("unroll") for (int k = 0; k < 2; ++k) dst[m][k] = *(const LAS bf16x8*)(lds + PG8_SA(b, h) + aoff + m * 2048 + k * 1024); } while (0)
; #define PG8_LDB(dst, b, h) do { _Pragma("unroll") for (int n = 0; n < 2; ++n) _Pragma("unroll") for (int k = 0; k < 2; ++k) dst[n][k] = *(const LAS bf16x8*)(lds + PG8_SB(b, h) + boff + n * 2048 + k * 1024); } while (0)
; #define PG8_MMA(ai, bj, At, Bt) do { __builtin_amdgcn_s_setprio(3); _Pragma("unroll") for (int m = 0; m < 4; ++m) _Pragma("unroll") for (int n = 0; n < 2; ++n) _Pragma("unroll") for (int k = 0; k < 2; ++k) \
;         acc[ai][bj][m][n] = __builtin_amdgcn_mfma_f32_16x16x32_bf16(Bt[n][k], At[m][k], acc[ai][bj][m][n], 0, 0, 0); __builtin_amdgcn_s_setprio(0); } while (0)
; #define PG8_WAIT_V(n) asm volatile("s_waitcnt vmcnt(" #n ")" ::: "memory")
; #define PG8_WAIT_L(n) asm volatile("s_waitcnt lgkmcnt(" #n ")" ::: "memory")
; #define PG8_BAR __builtin_amdgcn_s_barrier()
; #define PG8_SCHED __builtin_amdgcn_sched_barrier(0)
; template <class Epi, class Sched, bool ALIGN_EPI = false, bool SP2 = false>
; __device__ __forceinline__ void gemm_phase(LAS unsigned char* lds, const Gemm g, const Sched& S, const Epi& E) {
;     ...
;             PG8_LDB(B0, 0, 0); PG8_LDB(B1, 0, 1); PG8_SCHED; PG8_LDA(At, 0, 0); PG8_STAGE(PG8_SA(1, 1), a1 + hsA, voffA);
;             PG8_WAIT_V(8); PG8_WAIT_L(0); PG8_BAR; PG8_MMA(0, 0, At, B0); PG8_MMA(0, 1, At, B1); PG8_BAR; PG8_SCHED;
;             PG8_LDA(At, 0, 1); PG8_STAGE(PG8_SB(0, 0), b2, voffB); PG8_STAGE(PG8_SB(0, 1), b2 + hsB, voffB); PG8_STAGE(PG8_SA(0, 0), a2, voffA);
;             PG8_WAIT_V(8); PG8_WAIT_L(0); PG8_BAR; PG8_MMA(1, 0, At, B0); PG8_MMA(1, 1, At, B1); PG8_BAR; PG8_SCHED;
.LBB0_309:
	ds_read_b128 v[112:115], v175
	ds_read_b128 v[132:135], v175 offset:1024
	ds_read_b128 v[136:139], v175 offset:2048
	ds_read_b128 v[140:143], v175 offset:3072
	ds_read_b128 v[144:147], v176
	ds_read_b128 v[148:151], v176 offset:1024
	ds_read_b128 v[184:187], v176 offset:2048
	ds_read_b128 v[188:191], v176 offset:3072
	s_add_u32 s24, s4, 0xffefc080
	s_addc_u32 s25, s5, -1
	s_cmp_eq_u32 s73, 60
	s_cselect_b32 s27, s11, s25
	s_cselect_b32 s26, s10, s24
	s_cselect_b32 s25, s21, s72
	s_cselect_b32 s24, s20, s71
	s_sub_u32 s100, s4, 0x104000
	s_subb_u32 s101, s5, 0
	v_lshl_add_u64 v[242:243], s[100:101], 0, v[152:153]
	s_mov_b32 m0, s42
	v_lshl_add_u64 v[244:245], s[100:101], 0, v[156:157]
	global_load_lds_dwordx4 v[242:243], off
	s_mov_b32 m0, s43
	s_nop 0
	global_load_lds_dwordx4 v[244:245], off
	v_lshl_add_u64 v[200:201], s[4:5], 0, v[164:165]
	s_add_i32 m0, s36, 0xc000
	ds_read_b128 v[192:195], v177
	ds_read_b128 v[196:199], v177 offset:1024
	ds_read_b128 v[206:209], v177 offset:2048
	ds_read_b128 v[210:213], v177 offset:3072
	ds_read_b128 v[214:217], v177 offset:4096
	ds_read_b128 v[218:221], v177 offset:5120
	ds_read_b128 v[222:225], v177 offset:6144
	ds_read_b128 v[226:229], v177 offset:7168
	global_load_lds_dwordx4 v[200:201], off
	v_lshl_add_u64 v[200:201], s[4:5], 0, v[166:167]
	s_add_i32 m0, s36, 0xe000
	s_nop 0
	global_load_lds_dwordx4 v[200:201], off
	s_waitcnt vmcnt(8)
	s_waitcnt lgkmcnt(0)
	s_barrier
	s_setprio 3
	s_waitcnt lgkmcnt(0)
	v_mfma_f32_16x16x32_bf16 v[128:131], v[112:115], v[192:195], v[128:131]
	v_mfma_f32_16x16x32_bf16 v[124:127], v[136:139], v[192:195], v[124:127]
	v_mfma_f32_16x16x32_bf16 v[108:111], v[112:115], v[206:209], v[108:111]
	v_mfma_f32_16x16x32_bf16 v[104:107], v[136:139], v[206:209], v[104:107]
	v_mfma_f32_16x16x32_bf16 v[92:95], v[112:115], v[214:217], v[92:95]
	v_mfma_f32_16x16x32_bf16 v[88:91], v[136:139], v[214:217], v[88:91]
	v_mfma_f32_16x16x32_bf16 v[76:79], v[112:115], v[222:225], v[76:79]
	v_mfma_f32_16x16x32_bf16 v[72:75], v[136:139], v[222:225], v[72:75]
	v_mfma_f32_16x16x32_bf16 v[128:131], v[132:135], v[196:199], v[128:131]
	v_mfma_f32_16x16x32_bf16 v[124:127], v[140:143], v[196:199], v[124:127]
	v_mfma_f32_16x16x32_bf16 v[108:111], v[132:135], v[210:213], v[108:111]
	v_mfma_f32_16x16x32_bf16 v[104:107], v[140:143], v[210:213], v[104:107]
	v_mfma_f32_16x16x32_bf16 v[92:95], v[132:135], v[218:221], v[92:95]
	v_mfma_f32_16x16x32_bf16 v[88:91], v[140:143], v[218:221], v[88:91]
	v_mfma_f32_16x16x32_bf16 v[76:79], v[132:135], v[226:229], v[76:79]
	v_mfma_f32_16x16x32_bf16 v[72:75], v[140:143], v[226:229], v[72:75]
	s_setprio 0
	s_setprio 3
	v_mfma_f32_16x16x32_bf16 v[120:123], v[144:147], v[192:195], v[120:123]
	v_mfma_f32_16x16x32_bf16 v[116:119], v[184:187], v[192:195], v[116:119]
	v_mfma_f32_16x16x32_bf16 v[100:103], v[144:147], v[206:209], v[100:103]
	v_mfma_f32_16x16x32_bf16 v[96:99], v[184:187], v[206:209], v[96:99]
	v_mfma_f32_16x16x32_bf16 v[84:87], v[144:147], v[214:217], v[84:87]
	v_mfma_f32_16x16x32_bf16 v[80:83], v[184:187], v[214:217], v[80:83]
	v_mfma_f32_16x16x32_bf16 v[68:71], v[144:147], v[222:225], v[68:71]
	v_mfma_f32_16x16x32_bf16 v[64:67], v[184:187], v[222:225], v[64:67]
	v_mfma_f32_16x16x32_bf16 v[120:123], v[148:151], v[196:199], v[120:123]
	v_mfma_f32_16x16x32_bf16 v[116:119], v[188:191], v[196:199], v[116:119]
	v_mfma_f32_16x16x32_bf16 v[100:103], v[148:151], v[210:213], v[100:103]
	v_mfma_f32_16x16x32_bf16 v[96:99], v[188:191], v[210:213], v[96:99]
	v_mfma_f32_16x16x32_bf16 v[84:87], v[148:151], v[218:221], v[84:87]
	v_mfma_f32_16x16x32_bf16 v[80:83], v[188:191], v[218:221], v[80:83]
	v_mfma_f32_16x16x32_bf16 v[68:71], v[148:151], v[226:229], v[68:71]
	v_mfma_f32_16x16x32_bf16 v[64:67], v[188:191], v[226:229], v[64:67]
	s_setprio 0
	s_barrier
	s_add_i32 s74, s45, s31
	v_lshl_add_u64 v[200:201], s[24:25], 0, v[154:155]
	s_mov_b32 m0, s74
	ds_read_b128 v[192:195], v177 offset:16384
	ds_read_b128 v[196:199], v177 offset:17408
	ds_read_b128 v[206:209], v177 offset:18432
	ds_read_b128 v[210:213], v177 offset:19456
	ds_read_b128 v[214:217], v177 offset:20480
	ds_read_b128 v[218:221], v177 offset:21504
	ds_read_b128 v[222:225], v177 offset:22528
	ds_read_b128 v[226:229], v177 offset:23552
	global_load_lds_dwordx4 v[200:201], off
	s_add_i32 m0, s74, 0x2000
	s_add_u32 s74, s24, 0x41000
	v_lshl_add_u64 v[230:231], s[24:25], 0, v[158:159]
	s_addc_u32 s75, s25, 0
	s_add_i32 s78, s46, s31
	global_load_lds_dwordx4 v[230:231], off
	v_lshl_add_u64 v[232:233], s[74:75], 0, v[154:155]
	s_mov_b32 m0, s78
	s_nop 0
	global_load_lds_dwordx4 v[232:233], off
	v_lshl_add_u64 v[232:233], s[74:75], 0, v[158:159]
	s_add_i32 m0, s78, 0x2000
	s_nop 0
	global_load_lds_dwordx4 v[232:233], off
	s_waitcnt vmcnt(6)
	s_waitcnt lgkmcnt(0)
	s_barrier
; #define PG8_STAGE(bufoff, gbase, voff) do { _Pragma("unroll") for (int _i = 0; _i < 2; ++_i) \
;         __builtin_amdgcn_global_load_lds((const unsigned*)((const char*)(gbase) + (voff)[_i]), (LAS unsigned*)(lds + (bufoff) + ldsw + _i * 8192), 16, 0, 0); } while (0)
; #define PG8_LDA(dst, b, h) do { _Pragma("unroll") for (int m = 0; m < 4; ++m) _Pragma("unroll") for (int k = 0; k < 2; ++k) dst[m][k] = *(const LAS bf16x8*)(lds + PG8_SA(b, h) + aoff + m * 2048 + k * 1024); } while (0)
; #define PG8_LDB(dst, b, h) do { _Pragma("unroll") for (int n = 0; n < 2; ++n) _Pragma("unroll") for (int k = 0; k < 2; ++k) dst[n][k] = *(const LAS bf16x8*)(lds + PG8_SB(b, h) + boff + n * 2048 + k * 1024); } while (0)
; #define PG8_MMA(ai, bj, At, Bt) do { __builtin_amdgcn_s_setprio(3); _Pragma("unroll") for (int m = 0; m < 4; ++m) _Pragma("unroll") for (int n = 0; n < 2; ++n) _Pragma("unroll") for (int k = 0; k < 2; ++k) \
;         acc[ai][bj][m][n] = __builtin_amdgcn_mfma_f32_16x16x32_bf16(Bt[n][k], At[m][k], acc[ai][bj][m][n], 0, 0, 0); __builtin_amdgcn_s_setprio(0); } while (0)
; #define PG8_WAIT_V(n) asm volatile("s_waitcnt vmcnt(" #n ")" ::: "memory")
; #define PG8_WAIT_L(n) asm volatile("s_waitcnt lgkmcnt(" #n ")" ::: "memory")
; #define PG8_BAR __builtin_amdgcn_s_barrier()
; #define PG8_SCHED __builtin_amdgcn_sched_barrier(0)
; template <class Epi, class Sched, bool ALIGN_EPI = false, bool SP2 = false>
; __device__ __forceinline__ void gemm_phase(LAS unsigned char* lds, const Gemm g, const Sched& S, const Epi& E) {
;     ...
;             PG8_WAIT_V(8); PG8_WAIT_L(0); PG8_BAR; PG8_MMA(1, 0, At, B0); PG8_MMA(1, 1, At, B1); PG8_BAR; PG8_SCHED;
;             PG8_LDB(B0, 1, 0); PG8_LDB(B1, 1, 1); PG8_SCHED; PG8_LDA(At, 1, 0); PG8_STAGE(PG8_SA(0, 1), a2 + hsA, voffA);
;             PG8_WAIT_V(8); PG8_WAIT_L(0); PG8_BAR; PG8_MMA(0, 0, At, B0); PG8_MMA(0, 1, At, B1); PG8_BAR; PG8_SCHED;
	s_setprio 3
	s_waitcnt lgkmcnt(0)
	v_mfma_f32_16x16x32_bf16 v[60:63], v[112:115], v[192:195], v[60:63]
	v_mfma_f32_16x16x32_bf16 v[56:59], v[136:139], v[192:195], v[56:59]
	v_mfma_f32_16x16x32_bf16 v[44:47], v[112:115], v[206:209], v[44:47]
	v_mfma_f32_16x16x32_bf16 v[40:43], v[136:139], v[206:209], v[40:43]
	v_mfma_f32_16x16x32_bf16 v[28:31], v[112:115], v[214:217], v[28:31]
	v_mfma_f32_16x16x32_bf16 v[24:27], v[136:139], v[214:217], v[24:27]
	v_mfma_f32_16x16x32_bf16 v[12:15], v[112:115], v[222:225], v[12:15]
	v_mfma_f32_16x16x32_bf16 v[8:11], v[136:139], v[222:225], v[8:11]
	v_mfma_f32_16x16x32_bf16 v[60:63], v[132:135], v[196:199], v[60:63]
	v_mfma_f32_16x16x32_bf16 v[56:59], v[140:143], v[196:199], v[56:59]
	v_mfma_f32_16x16x32_bf16 v[44:47], v[132:135], v[210:213], v[44:47]
	v_mfma_f32_16x16x32_bf16 v[40:43], v[140:143], v[210:213], v[40:43]
	v_mfma_f32_16x16x32_bf16 v[28:31], v[132:135], v[218:221], v[28:31]
	v_mfma_f32_16x16x32_bf16 v[24:27], v[140:143], v[218:221], v[24:27]
	v_mfma_f32_16x16x32_bf16 v[12:15], v[132:135], v[226:229], v[12:15]
	v_mfma_f32_16x16x32_bf16 v[8:11], v[140:143], v[226:229], v[8:11]
	s_setprio 0
	s_setprio 3
	v_mfma_f32_16x16x32_bf16 v[52:55], v[144:147], v[192:195], v[52:55]
	v_mfma_f32_16x16x32_bf16 v[48:51], v[184:187], v[192:195], v[48:51]
	v_mfma_f32_16x16x32_bf16 v[36:39], v[144:147], v[206:209], v[36:39]
	v_mfma_f32_16x16x32_bf16 v[32:35], v[184:187], v[206:209], v[32:35]
	v_mfma_f32_16x16x32_bf16 v[20:23], v[144:147], v[214:217], v[20:23]
	v_mfma_f32_16x16x32_bf16 v[16:19], v[184:187], v[214:217], v[16:19]
	v_mfma_f32_16x16x32_bf16 v[4:7], v[144:147], v[222:225], v[4:7]
	v_mfma_f32_16x16x32_bf16 v[0:3], v[184:187], v[222:225], v[0:3]
	v_mfma_f32_16x16x32_bf16 v[52:55], v[148:151], v[196:199], v[52:55]
	v_mfma_f32_16x16x32_bf16 v[48:51], v[188:191], v[196:199], v[48:51]
	v_mfma_f32_16x16x32_bf16 v[36:39], v[148:151], v[210:213], v[36:39]
	v_mfma_f32_16x16x32_bf16 v[32:35], v[188:191], v[210:213], v[32:35]
	v_mfma_f32_16x16x32_bf16 v[20:23], v[148:151], v[218:221], v[20:23]
	v_mfma_f32_16x16x32_bf16 v[16:19], v[188:191], v[218:221], v[16:19]
	v_mfma_f32_16x16x32_bf16 v[4:7], v[148:151], v[226:229], v[4:7]
	v_mfma_f32_16x16x32_bf16 v[0:3], v[188:191], v[226:229], v[0:3]
	s_setprio 0
	s_barrier
	s_add_i32 s74, 0, 0x18000
	s_add_i32 s75, 0, 0x1c000
	v_add_u32_e32 v140, s74, v173
	v_add_u32_e32 v188, s75, v173
	ds_read_b128 v[112:115], v140
	ds_read_b128 v[132:135], v140 offset:1024
	ds_read_b128 v[136:139], v140 offset:2048
	ds_read_b128 v[140:143], v140 offset:3072
	ds_read_b128 v[144:147], v188
	ds_read_b128 v[148:151], v188 offset:1024
	ds_read_b128 v[184:187], v188 offset:2048
	ds_read_b128 v[188:191], v188 offset:3072
	v_lshl_add_u64 v[242:243], s[26:27], 0, v[152:153]
	s_mov_b32 m0, s36
	v_lshl_add_u64 v[244:245], s[26:27], 0, v[156:157]
	global_load_lds_dwordx4 v[242:243], off
	s_mov_b32 m0, s37
	s_nop 0
	global_load_lds_dwordx4 v[244:245], off
	s_add_u32 s26, s26, 0x104000
	s_addc_u32 s27, s27, 0
	s_mov_b32 m0, s38
	v_lshl_add_u64 v[236:237], s[26:27], 0, v[152:153]
	ds_read_b128 v[192:195], v177 offset:32768
	ds_read_b128 v[196:199], v177 offset:33792
	ds_read_b128 v[206:209], v177 offset:34816
	ds_read_b128 v[210:213], v177 offset:35840
	ds_read_b128 v[214:217], v177 offset:36864
	ds_read_b128 v[218:221], v177 offset:37888
	ds_read_b128 v[222:225], v177 offset:38912
	ds_read_b128 v[226:229], v177 offset:39936
	global_load_lds_dwordx4 v[236:237], off
	v_lshl_add_u64 v[236:237], s[26:27], 0, v[156:157]
	s_mov_b32 m0, s39
	s_nop 0
	global_load_lds_dwordx4 v[236:237], off
	s_waitcnt vmcnt(8)
	s_waitcnt lgkmcnt(0)
	s_barrier
; #define PG8_STAGE(bufoff, gbase, voff) do { _Pragma("unroll") for (int _i = 0; _i < 2; ++_i) \
;         __builtin_amdgcn_global_load_lds((const unsigned*)((const char*)(gbase) + (voff)[_i]), (LAS unsigned*)(lds + (bufoff) + ldsw + _i * 8192), 16, 0, 0); } while (0)
; #define PG8_LDA(dst, b, h) do { _Pragma("unroll") for (int m = 0; m < 4; ++m) _Pragma("unroll") for (int k = 0; k < 2; ++k) dst[m][k] = *(const LAS bf16x8*)(lds + PG8_SA(b, h) + aoff + m * 2048 + k * 1024); } while (0)
; #define PG8_MMA(ai, bj, At, Bt) do { __builtin_amdgcn_s_setprio(3); _Pragma("unroll") for (int m = 0; m < 4; ++m) _Pragma("unroll") for (int n = 0; n < 2; ++n) _Pragma("unroll") for (int k = 0; k < 2; ++k) \
;         acc[ai][bj][m][n] = __builtin_amdgcn_mfma_f32_16x16x32_bf16(Bt[n][k], At[m][k], acc[ai][bj][m][n], 0, 0, 0); __builtin_amdgcn_s_setprio(0); } while (0)
; #define PG8_WAIT_V(n) asm volatile("s_waitcnt vmcnt(" #n ")" ::: "memory")
; #define PG8_WAIT_L(n) asm volatile("s_waitcnt lgkmcnt(" #n ")" ::: "memory")
; #define PG8_BAR __builtin_amdgcn_s_barrier()
; #define PG8_SCHED __builtin_amdgcn_sched_barrier(0)
; template <class Epi, class Sched, bool ALIGN_EPI = false, bool SP2 = false>
; __device__ __forceinline__ void gemm_phase(LAS unsigned char* lds, const Gemm g, const Sched& S, const Epi& E) {
;     ...
;         for (int t = 0; t < nt; t += 2) {
;     ...
;             PG8_WAIT_V(8); PG8_WAIT_L(0); PG8_BAR; PG8_MMA(0, 0, At, B0); PG8_MMA(0, 1, At, B1); PG8_BAR; PG8_SCHED;
;             PG8_LDA(At, 1, 1); PG8_STAGE(PG8_SB(1, 0), b3, voffB); PG8_STAGE(PG8_SB(1, 1), b3 + hsB, voffB); PG8_STAGE(PG8_SA(1, 0), a3, voffA);
;             PG8_WAIT_V(8); PG8_WAIT_L(0); PG8_BAR; PG8_MMA(1, 0, At, B0); PG8_MMA(1, 1, At, B1); PG8_BAR; PG8_SCHED;
	s_setprio 3
	s_waitcnt lgkmcnt(0)
	v_mfma_f32_16x16x32_bf16 v[128:131], v[112:115], v[192:195], v[128:131]
	v_mfma_f32_16x16x32_bf16 v[124:127], v[136:139], v[192:195], v[124:127]
	v_mfma_f32_16x16x32_bf16 v[108:111], v[112:115], v[206:209], v[108:111]
	v_mfma_f32_16x16x32_bf16 v[104:107], v[136:139], v[206:209], v[104:107]
	v_mfma_f32_16x16x32_bf16 v[92:95], v[112:115], v[214:217], v[92:95]
	v_mfma_f32_16x16x32_bf16 v[88:91], v[136:139], v[214:217], v[88:91]
	v_mfma_f32_16x16x32_bf16 v[76:79], v[112:115], v[222:225], v[76:79]
	v_mfma_f32_16x16x32_bf16 v[72:75], v[136:139], v[222:225], v[72:75]
	v_mfma_f32_16x16x32_bf16 v[128:131], v[132:135], v[196:199], v[128:131]
	v_mfma_f32_16x16x32_bf16 v[124:127], v[140:143], v[196:199], v[124:127]
	v_mfma_f32_16x16x32_bf16 v[108:111], v[132:135], v[210:213], v[108:111]
	v_mfma_f32_16x16x32_bf16 v[104:107], v[140:143], v[210:213], v[104:107]
	v_mfma_f32_16x16x32_bf16 v[92:95], v[132:135], v[218:221], v[92:95]
	v_mfma_f32_16x16x32_bf16 v[88:91], v[140:143], v[218:221], v[88:91]
	v_mfma_f32_16x16x32_bf16 v[76:79], v[132:135], v[226:229], v[76:79]
	v_mfma_f32_16x16x32_bf16 v[72:75], v[140:143], v[226:229], v[72:75]
	s_setprio 0
	s_setprio 3
	v_mfma_f32_16x16x32_bf16 v[120:123], v[144:147], v[192:195], v[120:123]
	v_mfma_f32_16x16x32_bf16 v[116:119], v[184:187], v[192:195], v[116:119]
	v_mfma_f32_16x16x32_bf16 v[100:103], v[144:147], v[206:209], v[100:103]
	v_mfma_f32_16x16x32_bf16 v[96:99], v[184:187], v[206:209], v[96:99]
	v_mfma_f32_16x16x32_bf16 v[84:87], v[144:147], v[214:217], v[84:87]
	v_mfma_f32_16x16x32_bf16 v[80:83], v[184:187], v[214:217], v[80:83]
	v_mfma_f32_16x16x32_bf16 v[68:71], v[144:147], v[222:225], v[68:71]
	v_mfma_f32_16x16x32_bf16 v[64:67], v[184:187], v[222:225], v[64:67]
	v_mfma_f32_16x16x32_bf16 v[120:123], v[148:151], v[196:199], v[120:123]
	v_mfma_f32_16x16x32_bf16 v[116:119], v[188:191], v[196:199], v[116:119]
	v_mfma_f32_16x16x32_bf16 v[100:103], v[148:151], v[210:213], v[100:103]
	v_mfma_f32_16x16x32_bf16 v[96:99], v[188:191], v[210:213], v[96:99]
	v_mfma_f32_16x16x32_bf16 v[84:87], v[148:151], v[218:221], v[84:87]
	v_mfma_f32_16x16x32_bf16 v[80:83], v[188:191], v[218:221], v[80:83]
	v_mfma_f32_16x16x32_bf16 v[68:71], v[148:151], v[226:229], v[68:71]
	v_mfma_f32_16x16x32_bf16 v[64:67], v[188:191], v[226:229], v[64:67]
	s_setprio 0
	s_barrier
	s_add_i32 s26, s74, s31
	v_lshl_add_u64 v[200:201], v[200:201], 0, s[14:15]
	s_mov_b32 m0, s26
	ds_read_b128 v[192:195], v177 offset:49152
	ds_read_b128 v[196:199], v177 offset:50176
	ds_read_b128 v[206:209], v177 offset:51200
	ds_read_b128 v[210:213], v177 offset:52224
	ds_read_b128 v[214:217], v177 offset:53248
	ds_read_b128 v[218:221], v177 offset:54272
	ds_read_b128 v[222:225], v177 offset:55296
	ds_read_b128 v[226:229], v177 offset:56320
	global_load_lds_dwordx4 v[200:201], off
	s_add_i32 m0, s26, 0x2000
	s_add_u32 s24, s24, 0x41080
	v_lshl_add_u64 v[200:201], v[230:231], 0, s[14:15]
	s_addc_u32 s25, s25, 0
	s_add_i32 s26, s75, s31
	global_load_lds_dwordx4 v[200:201], off
	v_lshl_add_u64 v[200:201], s[24:25], 0, v[154:155]
	s_mov_b32 m0, s26
	s_nop 0
	global_load_lds_dwordx4 v[200:201], off
	v_lshl_add_u64 v[200:201], s[24:25], 0, v[158:159]
	s_add_i32 m0, s26, 0x2000
	s_nop 0
	global_load_lds_dwordx4 v[200:201], off
	s_waitcnt vmcnt(6)
	s_waitcnt lgkmcnt(0)
	s_barrier
	s_setprio 3
	s_waitcnt lgkmcnt(0)
	v_mfma_f32_16x16x32_bf16 v[60:63], v[112:115], v[192:195], v[60:63]
	v_mfma_f32_16x16x32_bf16 v[56:59], v[136:139], v[192:195], v[56:59]
	v_mfma_f32_16x16x32_bf16 v[44:47], v[112:115], v[206:209], v[44:47]
	v_mfma_f32_16x16x32_bf16 v[40:43], v[136:139], v[206:209], v[40:43]
	v_mfma_f32_16x16x32_bf16 v[28:31], v[112:115], v[214:217], v[28:31]
	v_mfma_f32_16x16x32_bf16 v[24:27], v[136:139], v[214:217], v[24:27]
	v_mfma_f32_16x16x32_bf16 v[12:15], v[112:115], v[222:225], v[12:15]
	v_mfma_f32_16x16x32_bf16 v[8:11], v[136:139], v[222:225], v[8:11]
	v_mfma_f32_16x16x32_bf16 v[60:63], v[132:135], v[196:199], v[60:63]
	v_mfma_f32_16x16x32_bf16 v[56:59], v[140:143], v[196:199], v[56:59]
	v_mfma_f32_16x16x32_bf16 v[44:47], v[132:135], v[210:213], v[44:47]
	v_mfma_f32_16x16x32_bf16 v[40:43], v[140:143], v[210:213], v[40:43]
	v_mfma_f32_16x16x32_bf16 v[28:31], v[132:135], v[218:221], v[28:31]
	v_mfma_f32_16x16x32_bf16 v[24:27], v[140:143], v[218:221], v[24:27]
	v_mfma_f32_16x16x32_bf16 v[12:15], v[132:135], v[226:229], v[12:15]
	v_mfma_f32_16x16x32_bf16 v[8:11], v[140:143], v[226:229], v[8:11]
	s_setprio 0
	s_setprio 3
	v_mfma_f32_16x16x32_bf16 v[52:55], v[144:147], v[192:195], v[52:55]
	v_mfma_f32_16x16x32_bf16 v[48:51], v[184:187], v[192:195], v[48:51]
	v_mfma_f32_16x16x32_bf16 v[36:39], v[144:147], v[206:209], v[36:39]
	v_mfma_f32_16x16x32_bf16 v[32:35], v[184:187], v[206:209], v[32:35]
	v_mfma_f32_16x16x32_bf16 v[20:23], v[144:147], v[214:217], v[20:23]
	v_mfma_f32_16x16x32_bf16 v[16:19], v[184:187], v[214:217], v[16:19]
	v_mfma_f32_16x16x32_bf16 v[4:7], v[144:147], v[222:225], v[4:7]
	v_mfma_f32_16x16x32_bf16 v[0:3], v[184:187], v[222:225], v[0:3]
	v_mfma_f32_16x16x32_bf16 v[52:55], v[148:151], v[196:199], v[52:55]
	v_mfma_f32_16x16x32_bf16 v[48:51], v[188:191], v[196:199], v[48:51]
	v_mfma_f32_16x16x32_bf16 v[36:39], v[148:151], v[210:213], v[36:39]
	v_mfma_f32_16x16x32_bf16 v[32:35], v[188:191], v[210:213], v[32:35]
	v_mfma_f32_16x16x32_bf16 v[20:23], v[148:151], v[218:221], v[20:23]
	v_mfma_f32_16x16x32_bf16 v[16:19], v[188:191], v[218:221], v[16:19]
	v_mfma_f32_16x16x32_bf16 v[4:7], v[148:151], v[226:229], v[4:7]
	v_mfma_f32_16x16x32_bf16 v[0:3], v[188:191], v[226:229], v[0:3]
	s_setprio 0
	s_barrier
	s_add_i32 s73, s73, 2
	s_add_u32 s4, s4, 0x100
	s_addc_u32 s5, s5, 0
	s_add_u32 s71, s71, 0x100
	s_addc_u32 s72, s72, 0
	s_cmp_gt_u32 s73, 61
	s_cbranch_scc0 .LBB0_309
	s_and_b64 vcc, exec, s[16:17]
	s_cbranch_vccz .LBB0_312
	s_barrier

; #define PG8_STAGE(bufoff, gbase, voff) do { _Pragma("unroll") for (int _i = 0; _i < 2; ++_i) \
;         __builtin_amdgcn_global_load_lds((const unsigned*)((const char*)(gbase) + (voff)[_i]), (LAS unsigned*)(lds + (bufoff) + ldsw + _i * 8192), 16, 0, 0); } while (0)
; #define PG8_LDA(dst, b, h) do { _Pragma("unroll") for (int m = 0; m < 4; ++m) _Pragma("unroll") for (int k = 0; k < 2; ++k) dst[m][k] = *(const LAS bf16x8*)(lds + PG8_SA(b, h) + aoff + m * 2048 + k * 1024); } while (0)
; #define PG8_LDB(dst, b, h) do { _Pragma("unroll") for (int n = 0; n < 2; ++n) _Pragma("unroll") for (int k = 0; k < 2; ++k) dst[n][k] = *(const LAS bf16x8*)(lds + PG8_SB(b, h) + boff + n * 2048 + k * 1024); } while (0)
; #define PG8_MMA(ai, bj, At, Bt) do { __builtin_amdgcn_s_setprio(3); _Pragma("unroll") for (int m = 0; m < 4; ++m) _Pragma("unroll") for (int n = 0; n < 2; ++n) _Pragma("unroll") for (int k = 0; k < 2; ++k) \
;         acc[ai][bj][m][n] = __builtin_amdgcn_mfma_f32_16x16x32_bf16(Bt[n][k], At[m][k], acc[ai][bj][m][n], 0, 0, 0); __builtin_amdgcn_s_setprio(0); } while (0)
; #define PG8_WAIT_V(n) asm volatile("s_waitcnt vmcnt(" #n ")" ::: "memory")
; #define PG8_WAIT_L(n) asm volatile("s_waitcnt lgkmcnt(" #n ")" ::: "memory")
; #define PG8_BAR __builtin_amdgcn_s_barrier()
; #define PG8_SCHED __builtin_amdgcn_sched_barrier(0)
; template <class Epi, class Sched, bool ALIGN_EPI = false, bool SP2 = false>
; __device__ __forceinline__ void gemm_phase(LAS unsigned char* lds, const Gemm g, const Sched& S, const Epi& E) {
;     ...
;             PG8_LDB(B0, 0, 0); PG8_LDB(B1, 0, 1); PG8_SCHED; PG8_LDA(At, 0, 0); PG8_STAGE(PG8_SA(1, 1), a1 + hsA, voffA);
;             PG8_WAIT_V(8); PG8_WAIT_L(0); PG8_BAR; PG8_MMA(0, 0, At, B0); PG8_MMA(0, 1, At, B1); PG8_BAR; PG8_SCHED;
;             PG8_LDA(At, 0, 1); PG8_STAGE(PG8_SB(0, 0), b2, voffB); PG8_STAGE(PG8_SB(0, 1), b2 + hsB, voffB); PG8_STAGE(PG8_SA(0, 0), a2, voffA);
;             PG8_WAIT_V(8); PG8_WAIT_L(0); PG8_BAR; PG8_MMA(1, 0, At, B0); PG8_MMA(1, 1, At, B1); PG8_BAR; PG8_SCHED;
.LBB0_350:
	ds_read_b128 v[140:143], v149
	ds_read_b128 v[156:159], v149 offset:1024
	ds_read_b128 v[160:163], v149 offset:2048
	ds_read_b128 v[164:167], v149 offset:3072
	ds_read_b128 v[168:171], v150
	ds_read_b128 v[172:175], v150 offset:1024
	ds_read_b128 v[176:179], v150 offset:2048
	ds_read_b128 v[180:183], v150 offset:3072
	s_add_u32 s16, s14, 0xffbfc080
	s_addc_u32 s17, s15, -1
	s_cmpk_eq_i32 s50, 0xfc
	s_cselect_b32 s21, s5, s17
	s_cselect_b32 s20, s4, s16
	s_cselect_b32 s17, s13, s49
	s_cselect_b32 s16, s12, s48
	s_sub_u32 s100, s14, 0x404000
	s_subb_u32 s101, s15, 0
	v_lshl_add_u64 v[242:243], s[100:101], 0, v[128:129]
	s_mov_b32 m0, s33
	v_lshl_add_u64 v[244:245], s[100:101], 0, v[130:131]
	global_load_lds_dwordx4 v[242:243], off
	s_mov_b32 m0, s38
	s_nop 0
	global_load_lds_dwordx4 v[244:245], off
	v_lshl_add_u64 v[144:145], s[14:15], 0, v[132:133]
	s_add_i32 m0, s26, 0xc000
	ds_read_b128 v[184:187], v151
	ds_read_b128 v[188:191], v151 offset:1024
	ds_read_b128 v[192:195], v151 offset:2048
	ds_read_b128 v[196:199], v151 offset:3072
	ds_read_b128 v[200:203], v151 offset:4096
	ds_read_b128 v[204:207], v151 offset:5120
	ds_read_b128 v[208:211], v151 offset:6144
	ds_read_b128 v[212:215], v151 offset:7168
	global_load_lds_dwordx4 v[144:145], off
	v_lshl_add_u64 v[144:145], s[14:15], 0, v[134:135]
	s_add_i32 m0, s26, 0xe000
	s_nop 0
	global_load_lds_dwordx4 v[144:145], off
	s_waitcnt vmcnt(8)
	s_waitcnt lgkmcnt(0)
	s_barrier
	s_setprio 3
	s_waitcnt lgkmcnt(0)
	v_mfma_f32_16x16x32_bf16 v[124:127], v[140:143], v[184:187], v[124:127]
	v_mfma_f32_16x16x32_bf16 v[120:123], v[160:163], v[184:187], v[120:123]
	v_mfma_f32_16x16x32_bf16 v[108:111], v[140:143], v[192:195], v[108:111]
	v_mfma_f32_16x16x32_bf16 v[104:107], v[160:163], v[192:195], v[104:107]
	v_mfma_f32_16x16x32_bf16 v[92:95], v[140:143], v[200:203], v[92:95]
	v_mfma_f32_16x16x32_bf16 v[88:91], v[160:163], v[200:203], v[88:91]
	v_mfma_f32_16x16x32_bf16 v[76:79], v[140:143], v[208:211], v[76:79]
	v_mfma_f32_16x16x32_bf16 v[72:75], v[160:163], v[208:211], v[72:75]
	v_mfma_f32_16x16x32_bf16 v[124:127], v[156:159], v[188:191], v[124:127]
	v_mfma_f32_16x16x32_bf16 v[120:123], v[164:167], v[188:191], v[120:123]
	v_mfma_f32_16x16x32_bf16 v[108:111], v[156:159], v[196:199], v[108:111]
	v_mfma_f32_16x16x32_bf16 v[104:107], v[164:167], v[196:199], v[104:107]
	v_mfma_f32_16x16x32_bf16 v[92:95], v[156:159], v[204:207], v[92:95]
	v_mfma_f32_16x16x32_bf16 v[88:91], v[164:167], v[204:207], v[88:91]
	v_mfma_f32_16x16x32_bf16 v[76:79], v[156:159], v[212:215], v[76:79]
	v_mfma_f32_16x16x32_bf16 v[72:75], v[164:167], v[212:215], v[72:75]
	s_setprio 0
	s_setprio 3
	v_mfma_f32_16x16x32_bf16 v[116:119], v[168:171], v[184:187], v[116:119]
	v_mfma_f32_16x16x32_bf16 v[112:115], v[176:179], v[184:187], v[112:115]
	v_mfma_f32_16x16x32_bf16 v[100:103], v[168:171], v[192:195], v[100:103]
	v_mfma_f32_16x16x32_bf16 v[96:99], v[176:179], v[192:195], v[96:99]
	v_mfma_f32_16x16x32_bf16 v[84:87], v[168:171], v[200:203], v[84:87]
	v_mfma_f32_16x16x32_bf16 v[80:83], v[176:179], v[200:203], v[80:83]
	v_mfma_f32_16x16x32_bf16 v[68:71], v[168:171], v[208:211], v[68:71]
	v_mfma_f32_16x16x32_bf16 v[64:67], v[176:179], v[208:211], v[64:67]
	v_mfma_f32_16x16x32_bf16 v[116:119], v[172:175], v[188:191], v[116:119]
	v_mfma_f32_16x16x32_bf16 v[112:115], v[180:183], v[188:191], v[112:115]
	v_mfma_f32_16x16x32_bf16 v[100:103], v[172:175], v[196:199], v[100:103]
	v_mfma_f32_16x16x32_bf16 v[96:99], v[180:183], v[196:199], v[96:99]
	v_mfma_f32_16x16x32_bf16 v[84:87], v[172:175], v[204:207], v[84:87]
	v_mfma_f32_16x16x32_bf16 v[80:83], v[180:183], v[204:207], v[80:83]
	v_mfma_f32_16x16x32_bf16 v[68:71], v[172:175], v[212:215], v[68:71]
	v_mfma_f32_16x16x32_bf16 v[64:67], v[180:183], v[212:215], v[64:67]
	s_setprio 0
	s_barrier
	s_add_i32 s51, s41, s25
	v_lshl_add_u64 v[144:145], s[16:17], 0, v[128:129]
	s_mov_b32 m0, s51
	ds_read_b128 v[184:187], v151 offset:16384
	ds_read_b128 v[188:191], v151 offset:17408
	ds_read_b128 v[192:195], v151 offset:18432
	ds_read_b128 v[196:199], v151 offset:19456
	ds_read_b128 v[200:203], v151 offset:20480
	ds_read_b128 v[204:207], v151 offset:21504
	ds_read_b128 v[208:211], v151 offset:22528
	ds_read_b128 v[212:215], v151 offset:23552
	global_load_lds_dwordx4 v[144:145], off
	s_add_i32 m0, s51, 0x2000
	s_add_u32 s52, s16, 0x404000
	v_lshl_add_u64 v[216:217], s[16:17], 0, v[130:131]
	s_addc_u32 s53, s17, 0
	s_add_i32 s51, s42, s25
	global_load_lds_dwordx4 v[216:217], off
	v_lshl_add_u64 v[218:219], s[52:53], 0, v[128:129]
	s_mov_b32 m0, s51
	s_nop 0
	global_load_lds_dwordx4 v[218:219], off
	v_lshl_add_u64 v[218:219], s[52:53], 0, v[130:131]
	s_add_i32 m0, s51, 0x2000
	s_nop 0
	global_load_lds_dwordx4 v[218:219], off
	s_waitcnt vmcnt(6)
	s_waitcnt lgkmcnt(0)
	s_barrier
; #define PG8_STAGE(bufoff, gbase, voff) do { _Pragma("unroll") for (int _i = 0; _i < 2; ++_i) \
;         __builtin_amdgcn_global_load_lds((const unsigned*)((const char*)(gbase) + (voff)[_i]), (LAS unsigned*)(lds + (bufoff) + ldsw + _i * 8192), 16, 0, 0); } while (0)
; #define PG8_LDA(dst, b, h) do { _Pragma("unroll") for (int m = 0; m < 4; ++m) _Pragma("unroll") for (int k = 0; k < 2; ++k) dst[m][k] = *(const LAS bf16x8*)(lds + PG8_SA(b, h) + aoff + m * 2048 + k * 1024); } while (0)
; #define PG8_LDB(dst, b, h) do { _Pragma("unroll") for (int n = 0; n < 2; ++n) _Pragma("unroll") for (int k = 0; k < 2; ++k) dst[n][k] = *(const LAS bf16x8*)(lds + PG8_SB(b, h) + boff + n * 2048 + k * 1024); } while (0)
; #define PG8_MMA(ai, bj, At, Bt) do { __builtin_amdgcn_s_setprio(3); _Pragma("unroll") for (int m = 0; m < 4; ++m) _Pragma("unroll") for (int n = 0; n < 2; ++n) _Pragma("unroll") for (int k = 0; k < 2; ++k) \
;         acc[ai][bj][m][n] = __builtin_amdgcn_mfma_f32_16x16x32_bf16(Bt[n][k], At[m][k], acc[ai][bj][m][n], 0, 0, 0); __builtin_amdgcn_s_setprio(0); } while (0)
; #define PG8_WAIT_V(n) asm volatile("s_waitcnt vmcnt(" #n ")" ::: "memory")
; #define PG8_WAIT_L(n) asm volatile("s_waitcnt lgkmcnt(" #n ")" ::: "memory")
; #define PG8_BAR __builtin_amdgcn_s_barrier()
; #define PG8_SCHED __builtin_amdgcn_sched_barrier(0)
; template <class Epi, class Sched, bool ALIGN_EPI = false, bool SP2 = false>
; __device__ __forceinline__ void gemm_phase(LAS unsigned char* lds, const Gemm g, const Sched& S, const Epi& E) {
;     ...
;             PG8_WAIT_V(8); PG8_WAIT_L(0); PG8_BAR; PG8_MMA(1, 0, At, B0); PG8_MMA(1, 1, At, B1); PG8_BAR; PG8_SCHED;
;             PG8_LDB(B0, 1, 0); PG8_LDB(B1, 1, 1); PG8_SCHED; PG8_LDA(At, 1, 0); PG8_STAGE(PG8_SA(0, 1), a2 + hsA, voffA);
;             PG8_WAIT_V(8); PG8_WAIT_L(0); PG8_BAR; PG8_MMA(0, 0, At, B0); PG8_MMA(0, 1, At, B1); PG8_BAR; PG8_SCHED;
	s_setprio 3
	s_waitcnt lgkmcnt(0)
	v_mfma_f32_16x16x32_bf16 v[60:63], v[140:143], v[184:187], v[60:63]
	v_mfma_f32_16x16x32_bf16 v[56:59], v[160:163], v[184:187], v[56:59]
	v_mfma_f32_16x16x32_bf16 v[44:47], v[140:143], v[192:195], v[44:47]
	v_mfma_f32_16x16x32_bf16 v[40:43], v[160:163], v[192:195], v[40:43]
	v_mfma_f32_16x16x32_bf16 v[28:31], v[140:143], v[200:203], v[28:31]
	v_mfma_f32_16x16x32_bf16 v[24:27], v[160:163], v[200:203], v[24:27]
	v_mfma_f32_16x16x32_bf16 v[12:15], v[140:143], v[208:211], v[12:15]
	v_mfma_f32_16x16x32_bf16 v[8:11], v[160:163], v[208:211], v[8:11]
	v_mfma_f32_16x16x32_bf16 v[60:63], v[156:159], v[188:191], v[60:63]
	v_mfma_f32_16x16x32_bf16 v[56:59], v[164:167], v[188:191], v[56:59]
	v_mfma_f32_16x16x32_bf16 v[44:47], v[156:159], v[196:199], v[44:47]
	v_mfma_f32_16x16x32_bf16 v[40:43], v[164:167], v[196:199], v[40:43]
	v_mfma_f32_16x16x32_bf16 v[28:31], v[156:159], v[204:207], v[28:31]
	v_mfma_f32_16x16x32_bf16 v[24:27], v[164:167], v[204:207], v[24:27]
	v_mfma_f32_16x16x32_bf16 v[12:15], v[156:159], v[212:215], v[12:15]
	v_mfma_f32_16x16x32_bf16 v[8:11], v[164:167], v[212:215], v[8:11]
	s_setprio 0
	s_setprio 3
	v_mfma_f32_16x16x32_bf16 v[52:55], v[168:171], v[184:187], v[52:55]
	v_mfma_f32_16x16x32_bf16 v[48:51], v[176:179], v[184:187], v[48:51]
	v_mfma_f32_16x16x32_bf16 v[36:39], v[168:171], v[192:195], v[36:39]
	v_mfma_f32_16x16x32_bf16 v[32:35], v[176:179], v[192:195], v[32:35]
	v_mfma_f32_16x16x32_bf16 v[20:23], v[168:171], v[200:203], v[20:23]
	v_mfma_f32_16x16x32_bf16 v[16:19], v[176:179], v[200:203], v[16:19]
	v_mfma_f32_16x16x32_bf16 v[4:7], v[168:171], v[208:211], v[4:7]
	v_mfma_f32_16x16x32_bf16 v[0:3], v[176:179], v[208:211], v[0:3]
	v_mfma_f32_16x16x32_bf16 v[52:55], v[172:175], v[188:191], v[52:55]
	v_mfma_f32_16x16x32_bf16 v[48:51], v[180:183], v[188:191], v[48:51]
	v_mfma_f32_16x16x32_bf16 v[36:39], v[172:175], v[196:199], v[36:39]
	v_mfma_f32_16x16x32_bf16 v[32:35], v[180:183], v[196:199], v[32:35]
	v_mfma_f32_16x16x32_bf16 v[20:23], v[172:175], v[204:207], v[20:23]
	v_mfma_f32_16x16x32_bf16 v[16:19], v[180:183], v[204:207], v[16:19]
	v_mfma_f32_16x16x32_bf16 v[4:7], v[172:175], v[212:215], v[4:7]
	v_mfma_f32_16x16x32_bf16 v[0:3], v[180:183], v[212:215], v[0:3]
	s_setprio 0
	s_barrier
	s_add_i32 s51, 0, 0x18000
	v_add_u32_e32 v155, s51, v146
	s_add_i32 s52, 0, 0x1c000
	ds_read_b128 v[140:143], v155
	ds_read_b128 v[156:159], v155 offset:1024
	ds_read_b128 v[160:163], v155 offset:2048
	ds_read_b128 v[164:167], v155 offset:3072
	v_add_u32_e32 v155, s52, v146
	ds_read_b128 v[168:171], v155
	ds_read_b128 v[172:175], v155 offset:1024
	ds_read_b128 v[176:179], v155 offset:2048
	ds_read_b128 v[180:183], v155 offset:3072
	v_lshl_add_u64 v[242:243], s[20:21], 0, v[128:129]
	s_mov_b32 m0, s26
	v_lshl_add_u64 v[244:245], s[20:21], 0, v[130:131]
	global_load_lds_dwordx4 v[242:243], off
	s_mov_b32 m0, s27
	s_nop 0
	global_load_lds_dwordx4 v[244:245], off
	s_add_u32 s20, s20, 0x404000
	s_addc_u32 s21, s21, 0
	s_mov_b32 m0, s30
	v_lshl_add_u64 v[222:223], s[20:21], 0, v[128:129]
	ds_read_b128 v[184:187], v151 offset:32768
	ds_read_b128 v[188:191], v151 offset:33792
	ds_read_b128 v[192:195], v151 offset:34816
	ds_read_b128 v[196:199], v151 offset:35840
	ds_read_b128 v[200:203], v151 offset:36864
	ds_read_b128 v[204:207], v151 offset:37888
	ds_read_b128 v[208:211], v151 offset:38912
	ds_read_b128 v[212:215], v151 offset:39936
	global_load_lds_dwordx4 v[222:223], off
	v_lshl_add_u64 v[222:223], s[20:21], 0, v[130:131]
	s_mov_b32 m0, s31
	s_nop 0
	global_load_lds_dwordx4 v[222:223], off
	s_waitcnt vmcnt(8)
	s_waitcnt lgkmcnt(0)
	s_barrier
; #define PG8_STAGE(bufoff, gbase, voff) do { _Pragma("unroll") for (int _i = 0; _i < 2; ++_i) \
;         __builtin_amdgcn_global_load_lds((const unsigned*)((const char*)(gbase) + (voff)[_i]), (LAS unsigned*)(lds + (bufoff) + ldsw + _i * 8192), 16, 0, 0); } while (0)
; #define PG8_LDA(dst, b, h) do { _Pragma("unroll") for (int m = 0; m < 4; ++m) _Pragma("unroll") for (int k = 0; k < 2; ++k) dst[m][k] = *(const LAS bf16x8*)(lds + PG8_SA(b, h) + aoff + m * 2048 + k * 1024); } while (0)
; #define PG8_MMA(ai, bj, At, Bt) do { __builtin_amdgcn_s_setprio(3); _Pragma("unroll") for (int m = 0; m < 4; ++m) _Pragma("unroll") for (int n = 0; n < 2; ++n) _Pragma("unroll") for (int k = 0; k < 2; ++k) \
;         acc[ai][bj][m][n] = __builtin_amdgcn_mfma_f32_16x16x32_bf16(Bt[n][k], At[m][k], acc[ai][bj][m][n], 0, 0, 0); __builtin_amdgcn_s_setprio(0); } while (0)
; #define PG8_WAIT_V(n) asm volatile("s_waitcnt vmcnt(" #n ")" ::: "memory")
; #define PG8_WAIT_L(n) asm volatile("s_waitcnt lgkmcnt(" #n ")" ::: "memory")
; #define PG8_BAR __builtin_amdgcn_s_barrier()
; #define PG8_SCHED __builtin_amdgcn_sched_barrier(0)
; template <class Epi, class Sched, bool ALIGN_EPI = false, bool SP2 = false>
; __device__ __forceinline__ void gemm_phase(LAS unsigned char* lds, const Gemm g, const Sched& S, const Epi& E) {
;     ...
;         for (int t = 0; t < nt; t += 2) {
;     ...
;             PG8_WAIT_V(8); PG8_WAIT_L(0); PG8_BAR; PG8_MMA(0, 0, At, B0); PG8_MMA(0, 1, At, B1); PG8_BAR; PG8_SCHED;
;             PG8_LDA(At, 1, 1); PG8_STAGE(PG8_SB(1, 0), b3, voffB); PG8_STAGE(PG8_SB(1, 1), b3 + hsB, voffB); PG8_STAGE(PG8_SA(1, 0), a3, voffA);
;             PG8_WAIT_V(8); PG8_WAIT_L(0); PG8_BAR; PG8_MMA(1, 0, At, B0); PG8_MMA(1, 1, At, B1); PG8_BAR; PG8_SCHED;
	s_setprio 3
	s_waitcnt lgkmcnt(0)
	v_mfma_f32_16x16x32_bf16 v[124:127], v[140:143], v[184:187], v[124:127]
	v_mfma_f32_16x16x32_bf16 v[120:123], v[160:163], v[184:187], v[120:123]
	v_mfma_f32_16x16x32_bf16 v[108:111], v[140:143], v[192:195], v[108:111]
	v_mfma_f32_16x16x32_bf16 v[104:107], v[160:163], v[192:195], v[104:107]
	v_mfma_f32_16x16x32_bf16 v[92:95], v[140:143], v[200:203], v[92:95]
	v_mfma_f32_16x16x32_bf16 v[88:91], v[160:163], v[200:203], v[88:91]
	v_mfma_f32_16x16x32_bf16 v[76:79], v[140:143], v[208:211], v[76:79]
	v_mfma_f32_16x16x32_bf16 v[72:75], v[160:163], v[208:211], v[72:75]
	v_mfma_f32_16x16x32_bf16 v[124:127], v[156:159], v[188:191], v[124:127]
	v_mfma_f32_16x16x32_bf16 v[120:123], v[164:167], v[188:191], v[120:123]
	v_mfma_f32_16x16x32_bf16 v[108:111], v[156:159], v[196:199], v[108:111]
	v_mfma_f32_16x16x32_bf16 v[104:107], v[164:167], v[196:199], v[104:107]
	v_mfma_f32_16x16x32_bf16 v[92:95], v[156:159], v[204:207], v[92:95]
	v_mfma_f32_16x16x32_bf16 v[88:91], v[164:167], v[204:207], v[88:91]
	v_mfma_f32_16x16x32_bf16 v[76:79], v[156:159], v[212:215], v[76:79]
	v_mfma_f32_16x16x32_bf16 v[72:75], v[164:167], v[212:215], v[72:75]
	s_setprio 0
	s_setprio 3
	v_mfma_f32_16x16x32_bf16 v[116:119], v[168:171], v[184:187], v[116:119]
	v_mfma_f32_16x16x32_bf16 v[112:115], v[176:179], v[184:187], v[112:115]
	v_mfma_f32_16x16x32_bf16 v[100:103], v[168:171], v[192:195], v[100:103]
	v_mfma_f32_16x16x32_bf16 v[96:99], v[176:179], v[192:195], v[96:99]
	v_mfma_f32_16x16x32_bf16 v[84:87], v[168:171], v[200:203], v[84:87]
	v_mfma_f32_16x16x32_bf16 v[80:83], v[176:179], v[200:203], v[80:83]
	v_mfma_f32_16x16x32_bf16 v[68:71], v[168:171], v[208:211], v[68:71]
	v_mfma_f32_16x16x32_bf16 v[64:67], v[176:179], v[208:211], v[64:67]
	v_mfma_f32_16x16x32_bf16 v[116:119], v[172:175], v[188:191], v[116:119]
	v_mfma_f32_16x16x32_bf16 v[112:115], v[180:183], v[188:191], v[112:115]
	v_mfma_f32_16x16x32_bf16 v[100:103], v[172:175], v[196:199], v[100:103]
	v_mfma_f32_16x16x32_bf16 v[96:99], v[180:183], v[196:199], v[96:99]
	v_mfma_f32_16x16x32_bf16 v[84:87], v[172:175], v[204:207], v[84:87]
	v_mfma_f32_16x16x32_bf16 v[80:83], v[180:183], v[204:207], v[80:83]
	v_mfma_f32_16x16x32_bf16 v[68:71], v[172:175], v[212:215], v[68:71]
	v_mfma_f32_16x16x32_bf16 v[64:67], v[180:183], v[212:215], v[64:67]
	s_setprio 0
	s_barrier
	s_add_i32 s20, s51, s25
	v_lshl_add_u64 v[144:145], v[144:145], 0, s[8:9]
	s_mov_b32 m0, s20
	ds_read_b128 v[184:187], v151 offset:49152
	ds_read_b128 v[188:191], v151 offset:50176
	ds_read_b128 v[192:195], v151 offset:51200
	ds_read_b128 v[196:199], v151 offset:52224
	ds_read_b128 v[200:203], v151 offset:53248
	ds_read_b128 v[204:207], v151 offset:54272
	ds_read_b128 v[208:211], v151 offset:55296
	ds_read_b128 v[212:215], v151 offset:56320
	global_load_lds_dwordx4 v[144:145], off
	s_add_i32 m0, s20, 0x2000
	s_add_u32 s16, s16, 0x404080
	v_lshl_add_u64 v[144:145], v[216:217], 0, s[8:9]
	s_addc_u32 s17, s17, 0
	s_add_i32 s20, s52, s25
	global_load_lds_dwordx4 v[144:145], off
	v_lshl_add_u64 v[144:145], s[16:17], 0, v[128:129]
	s_mov_b32 m0, s20
	s_nop 0
	global_load_lds_dwordx4 v[144:145], off
	v_lshl_add_u64 v[144:145], s[16:17], 0, v[130:131]
	s_add_i32 m0, s20, 0x2000
	s_nop 0
	global_load_lds_dwordx4 v[144:145], off
	s_waitcnt vmcnt(6)
	s_waitcnt lgkmcnt(0)
	s_barrier
	s_setprio 3
	s_waitcnt lgkmcnt(0)
	v_mfma_f32_16x16x32_bf16 v[60:63], v[140:143], v[184:187], v[60:63]
	v_mfma_f32_16x16x32_bf16 v[56:59], v[160:163], v[184:187], v[56:59]
	v_mfma_f32_16x16x32_bf16 v[44:47], v[140:143], v[192:195], v[44:47]
	v_mfma_f32_16x16x32_bf16 v[40:43], v[160:163], v[192:195], v[40:43]
	v_mfma_f32_16x16x32_bf16 v[28:31], v[140:143], v[200:203], v[28:31]
	v_mfma_f32_16x16x32_bf16 v[24:27], v[160:163], v[200:203], v[24:27]
	v_mfma_f32_16x16x32_bf16 v[12:15], v[140:143], v[208:211], v[12:15]
	v_mfma_f32_16x16x32_bf16 v[8:11], v[160:163], v[208:211], v[8:11]
	v_mfma_f32_16x16x32_bf16 v[60:63], v[156:159], v[188:191], v[60:63]
	v_mfma_f32_16x16x32_bf16 v[56:59], v[164:167], v[188:191], v[56:59]
	v_mfma_f32_16x16x32_bf16 v[44:47], v[156:159], v[196:199], v[44:47]
	v_mfma_f32_16x16x32_bf16 v[40:43], v[164:167], v[196:199], v[40:43]
	v_mfma_f32_16x16x32_bf16 v[28:31], v[156:159], v[204:207], v[28:31]
	v_mfma_f32_16x16x32_bf16 v[24:27], v[164:167], v[204:207], v[24:27]
	v_mfma_f32_16x16x32_bf16 v[12:15], v[156:159], v[212:215], v[12:15]
	v_mfma_f32_16x16x32_bf16 v[8:11], v[164:167], v[212:215], v[8:11]
	s_setprio 0
	s_setprio 3
	v_mfma_f32_16x16x32_bf16 v[52:55], v[168:171], v[184:187], v[52:55]
	v_mfma_f32_16x16x32_bf16 v[48:51], v[176:179], v[184:187], v[48:51]
	v_mfma_f32_16x16x32_bf16 v[36:39], v[168:171], v[192:195], v[36:39]
	v_mfma_f32_16x16x32_bf16 v[32:35], v[176:179], v[192:195], v[32:35]
	v_mfma_f32_16x16x32_bf16 v[20:23], v[168:171], v[200:203], v[20:23]
	v_mfma_f32_16x16x32_bf16 v[16:19], v[176:179], v[200:203], v[16:19]
	v_mfma_f32_16x16x32_bf16 v[4:7], v[168:171], v[208:211], v[4:7]
	v_mfma_f32_16x16x32_bf16 v[0:3], v[176:179], v[208:211], v[0:3]
	v_mfma_f32_16x16x32_bf16 v[52:55], v[172:175], v[188:191], v[52:55]
	v_mfma_f32_16x16x32_bf16 v[48:51], v[180:183], v[188:191], v[48:51]
	v_mfma_f32_16x16x32_bf16 v[36:39], v[172:175], v[196:199], v[36:39]
	v_mfma_f32_16x16x32_bf16 v[32:35], v[180:183], v[196:199], v[32:35]
	v_mfma_f32_16x16x32_bf16 v[20:23], v[172:175], v[204:207], v[20:23]
	v_mfma_f32_16x16x32_bf16 v[16:19], v[180:183], v[204:207], v[16:19]
	v_mfma_f32_16x16x32_bf16 v[4:7], v[172:175], v[212:215], v[4:7]
	v_mfma_f32_16x16x32_bf16 v[0:3], v[180:183], v[212:215], v[0:3]
	s_setprio 0
	s_barrier
	s_add_i32 s50, s50, 2
	s_add_u32 s14, s14, 0x100
	s_addc_u32 s15, s15, 0
	s_add_u32 s48, s48, 0x100
	s_addc_u32 s49, s49, 0
	s_cmpk_gt_u32 s50, 0xfd
	s_cbranch_scc0 .LBB0_350
	s_and_b64 vcc, exec, s[10:11]
	s_cbranch_vccz .LBB0_353
	s_barrier

; __global__ void __launch_bounds__(NWAVES * 64, 2) fwd_mega(Args args) {
	.amdhsa_kernel _Z8fwd_mega4Args
		.amdhsa_group_segment_fixed_size 0
		.amdhsa_private_segment_fixed_size 0
		.amdhsa_kernarg_size 408
		.amdhsa_user_sgpr_count 2
		.amdhsa_user_sgpr_dispatch_ptr 0
		.amdhsa_user_sgpr_queue_ptr 0
		.amdhsa_user_sgpr_kernarg_segment_ptr 1
		.amdhsa_user_sgpr_dispatch_id 0
		.amdhsa_user_sgpr_kernarg_preload_length 0
		.amdhsa_user_sgpr_kernarg_preload_offset 0
		.amdhsa_user_sgpr_private_segment_size 0
		.amdhsa_uses_dynamic_stack 0
		.amdhsa_enable_private_segment 0
		.amdhsa_system_sgpr_workgroup_id_x 1
		.amdhsa_system_sgpr_workgroup_id_y 0
		.amdhsa_system_sgpr_workgroup_id_z 0
		.amdhsa_system_sgpr_workgroup_info 0
		.amdhsa_system_vgpr_workitem_id 2
		.amdhsa_next_free_vgpr 248
		.amdhsa_next_free_sgpr 102
		.amdhsa_accum_offset 248
		.amdhsa_reserve_vcc 1
		.amdhsa_float_round_mode_32 0
		.amdhsa_float_round_mode_16_64 0
		.amdhsa_float_denorm_mode_32 3
		.amdhsa_float_denorm_mode_16_64 3
		.amdhsa_dx10_clamp 1
		.amdhsa_ieee_mode 1
		.amdhsa_fp16_overflow 0
		.amdhsa_tg_split 0
		.amdhsa_exception_fp_ieee_invalid_op 0
		.amdhsa_exception_fp_denorm_src 0
		.amdhsa_exception_fp_ieee_div_zero 0
		.amdhsa_exception_fp_ieee_overflow 0
		.amdhsa_exception_fp_ieee_underflow 0
		.amdhsa_exception_fp_ieee_inexact 0
		.amdhsa_exception_int_div_zero 0
	.end_amdhsa_kernel

; __global__ void __launch_bounds__(NWAVES * 64, 2) fwd_mega(Args args) {
amdhsa.kernels:
  - .agpr_count:     0
    .args:
      - .offset:         0
        .size:           152
        .value_kind:     by_value
      - .offset:         152
        .size:           4
        .value_kind:     hidden_block_count_x
      - .offset:         156
        .size:           4
        .value_kind:     hidden_block_count_y
      - .offset:         160
        .size:           4
        .value_kind:     hidden_block_count_z
      - .offset:         164
        .size:           2
        .value_kind:     hidden_group_size_x
      - .offset:         166
        .size:           2
        .value_kind:     hidden_group_size_y
      - .offset:         168
        .size:           2
        .value_kind:     hidden_group_size_z
      - .offset:         170
        .size:           2
        .value_kind:     hidden_remainder_x
      - .offset:         172
        .size:           2
        .value_kind:     hidden_remainder_y
      - .offset:         174
        .size:           2
        .value_kind:     hidden_remainder_z
      - .offset:         192
        .size:           8
        .value_kind:     hidden_global_offset_x
      - .offset:         200
        .size:           8
        .value_kind:     hidden_global_offset_y
      - .offset:         208
        .size:           8
        .value_kind:     hidden_global_offset_z
      - .offset:         216
        .size:           2
        .value_kind:     hidden_grid_dims
      - .offset:         240
        .size:           8
        .value_kind:     hidden_multigrid_sync_arg
      - .offset:         272
        .size:           4
        .value_kind:     hidden_dynamic_lds_size
    .group_segment_fixed_size: 0
    .kernarg_segment_align: 8
    .kernarg_segment_size: 408
    .language:       OpenCL C
    .language_version:
      - 2
      - 0
    .max_flat_workgroup_size: 512
    .name:           _Z8fwd_mega4Args
    .private_segment_fixed_size: 0
    .sgpr_count:     108
    .sgpr_spill_count: 0
    .symbol:         _Z8fwd_mega4Args.kd
    .uniform_work_group_size: 1
    .uses_dynamic_stack: false
    .vgpr_count:     248
    .vgpr_spill_count: 0
    .wavefront_size: 64
